# v4: + conv LayerNorm chains interleaved across 8 tokens + GEMM accumulator clears replaced by SrcC=0 in a peeled first K iteration; bit-exact
# speedup vs baseline: 1.0090x; 1.0045x over previous
; __device__ __forceinline__ void conv_phase(LAS unsigned char* lds, const bf16_t* P, const float* cw, const float* cb, const float* ng, const float* nb, bf16_t* CAT, int bid, int G, const int tid) {
;     ...
;             const int c = tid & 127, tb = tid >> 7;
;             float wj[31];
; #pragma unroll
;             for (int j = 0; j < 31; ++j) wj[j] = cw[j * 1024 + g * 128 + c];
;             const float bias = cb[g * 128 + c];
;             float acc[16];
; #pragma unroll
;             for (int o = 0; o < 16; ++o) acc[o] = bias;
; #pragma unroll
;             for (int i = 0; i < 46; ++i) {
;                 const float z = zs[(tb * 16 + i) * 128 + c];
; #pragma unroll
;                 for (int o = 0; o < 16; ++o) { const int j = i - o; if (j >= 0 && j <= 30) acc[o] += wj[j] * z; }
;             }
.LBB0_170:
	s_and_b32 s30, s35, 0x380
	v_or_b32_e32 v31, s30, v39
	v_lshlrev_b32_e32 v176, 2, v31
	v_lshl_add_u64 v[32:33], s[4:5], 0, v[176:177]
	v_add_co_u32_e32 v34, vcc, 0x1000, v32
	flat_load_dword v107, v[32:33]
	s_nop 0
	v_addc_co_u32_e32 v35, vcc, 0, v33, vcc
	flat_load_dword v105, v[34:35]
	v_add_co_u32_e32 v34, vcc, 0x2000, v32
	s_mov_b32 s26, 0xa000
	s_nop 0
	v_addc_co_u32_e32 v35, vcc, 0, v33, vcc
	flat_load_dword v104, v[34:35]
	v_add_co_u32_e32 v34, vcc, 0x3000, v32
	v_lshl_add_u64 v[86:87], s[6:7], 0, v[176:177]
	s_nop 0
	v_addc_co_u32_e32 v35, vcc, 0, v33, vcc
	flat_load_dword v101, v[34:35]
	v_add_co_u32_e32 v34, vcc, 0x4000, v32
	ds_read2st64_b32 v[90:91], v40 offset0:12 offset1:14
	s_nop 0
	v_addc_co_u32_e32 v35, vcc, 0, v33, vcc
	flat_load_dword v100, v[34:35]
	v_add_co_u32_e32 v34, vcc, 0x5000, v32
	ds_read2st64_b32 v[94:95], v40 offset0:16 offset1:18
	s_nop 0
	v_addc_co_u32_e32 v35, vcc, 0, v33, vcc
	flat_load_dword v97, v[34:35]
	v_add_co_u32_e32 v34, vcc, 0x6000, v32
	ds_read2st64_b32 v[98:99], v40 offset0:20 offset1:22
	s_nop 0
	v_addc_co_u32_e32 v35, vcc, 0, v33, vcc
	flat_load_dword v96, v[34:35]
	v_add_co_u32_e32 v34, vcc, 0x7000, v32
	ds_read2st64_b32 v[102:103], v40 offset0:24 offset1:26
	s_nop 0
	v_addc_co_u32_e32 v35, vcc, 0, v33, vcc
	flat_load_dword v93, v[34:35]
	v_add_co_u32_e32 v34, vcc, s72, v32
	ds_read2st64_b32 v[108:109], v40 offset0:28 offset1:30
	s_nop 0
	v_addc_co_u32_e32 v35, vcc, 0, v33, vcc
	flat_load_dword v92, v[34:35]
	v_add_co_u32_e32 v34, vcc, 0x9000, v32
	s_and_b32 s31, s34, 0xffffffc0
	s_nop 0
	v_addc_co_u32_e32 v35, vcc, 0, v33, vcc
	flat_load_dword v89, v[34:35]
	v_add_co_u32_e32 v34, vcc, s26, v32
	s_mov_b32 s26, 0xe000
	s_nop 0
	v_addc_co_u32_e32 v35, vcc, 0, v33, vcc
	flat_load_dword v88, v[34:35]
	v_add_co_u32_e32 v34, vcc, 0xb000, v32
	s_mov_b32 s34, s15
	s_nop 0
	v_addc_co_u32_e32 v35, vcc, 0, v33, vcc
	flat_load_dword v85, v[34:35]
	v_add_co_u32_e32 v34, vcc, s73, v32
	s_mov_b32 s35, s17
	s_nop 0
	v_addc_co_u32_e32 v35, vcc, 0, v33, vcc
	flat_load_dword v82, v[34:35]
	v_add_co_u32_e32 v34, vcc, 0xd000, v32
	s_nop 1
	v_addc_co_u32_e32 v35, vcc, 0, v33, vcc
	flat_load_dword v81, v[34:35]
	v_add_co_u32_e32 v34, vcc, s26, v32
	s_mov_b32 s26, 0xf000
	s_nop 0
	v_addc_co_u32_e32 v35, vcc, 0, v33, vcc
	flat_load_dword v80, v[34:35]
	v_add_co_u32_e32 v34, vcc, s26, v32
	s_mov_b32 s26, 0x10000
	s_nop 0
	v_addc_co_u32_e32 v35, vcc, 0, v33, vcc
	flat_load_dword v79, v[34:35]
	v_add_co_u32_e32 v34, vcc, s26, v32
	s_mov_b32 s26, 0x11000
	s_nop 0
	v_addc_co_u32_e32 v35, vcc, 0, v33, vcc
	flat_load_dword v78, v[34:35]
	v_add_co_u32_e32 v34, vcc, s26, v32
	s_mov_b32 s26, 0x12000
	s_nop 0
	v_addc_co_u32_e32 v35, vcc, 0, v33, vcc
	flat_load_dword v77, v[34:35]
	v_add_co_u32_e32 v34, vcc, s26, v32
	s_mov_b32 s26, 0x13000
	s_nop 0
	v_addc_co_u32_e32 v35, vcc, 0, v33, vcc
	flat_load_dword v76, v[34:35]
	v_add_co_u32_e32 v34, vcc, s26, v32
	s_mov_b32 s26, 0x14000
	s_nop 0
	v_addc_co_u32_e32 v35, vcc, 0, v33, vcc
	flat_load_dword v73, v[34:35]
	v_add_co_u32_e32 v34, vcc, s26, v32
	s_mov_b32 s26, 0x15000
	s_nop 0
	v_addc_co_u32_e32 v35, vcc, 0, v33, vcc
	flat_load_dword v72, v[34:35]
	v_add_co_u32_e32 v34, vcc, s26, v32
	s_mov_b32 s26, 0x16000
	s_nop 0
	v_addc_co_u32_e32 v35, vcc, 0, v33, vcc
	flat_load_dword v71, v[34:35]
	v_add_co_u32_e32 v34, vcc, s26, v32
	s_mov_b32 s26, 0x17000
	s_nop 0
	v_addc_co_u32_e32 v35, vcc, 0, v33, vcc
	flat_load_dword v70, v[34:35]
	v_add_co_u32_e32 v34, vcc, s26, v32
	s_mov_b32 s26, 0x18000
	s_nop 0
	v_addc_co_u32_e32 v35, vcc, 0, v33, vcc
	flat_load_dword v69, v[34:35]
	v_add_co_u32_e32 v34, vcc, s26, v32
	s_mov_b32 s26, 0x19000
	s_nop 0
	v_addc_co_u32_e32 v35, vcc, 0, v33, vcc
	flat_load_dword v68, v[34:35]
	v_add_co_u32_e32 v34, vcc, s26, v32
	s_mov_b32 s26, 0x1a000
	s_nop 0
	v_addc_co_u32_e32 v35, vcc, 0, v33, vcc
	flat_load_dword v67, v[34:35]
	v_add_co_u32_e32 v34, vcc, s26, v32
	s_mov_b32 s26, 0x1b000
	s_nop 0
	v_addc_co_u32_e32 v35, vcc, 0, v33, vcc
	flat_load_dword v66, v[34:35]
	v_add_co_u32_e32 v34, vcc, s26, v32
	s_mov_b32 s26, 0x1c000
	s_nop 0
	v_addc_co_u32_e32 v35, vcc, 0, v33, vcc
	v_add_co_u32_e32 v74, vcc, s26, v32
	s_mov_b32 s26, 0x1d000
	s_nop 0
	v_addc_co_u32_e32 v75, vcc, 0, v33, vcc
	flat_load_dword v34, v[34:35]
	s_nop 0
	flat_load_dword v35, v[74:75]
	v_add_co_u32_e32 v74, vcc, s26, v32
	s_mov_b32 s26, 0x1e000
	s_nop 0
	v_addc_co_u32_e32 v75, vcc, 0, v33, vcc
	v_add_co_u32_e32 v32, vcc, s26, v32
	flat_load_dword v31, v[74:75]
	s_nop 0
	v_addc_co_u32_e32 v33, vcc, 0, v33, vcc
	flat_load_dword v32, v[32:33]
	ds_read2st64_b32 v[74:75], v40 offset1:2
	flat_load_dword v33, v[86:87]
	ds_read2st64_b32 v[86:87], v40 offset0:4 offset1:6
	s_lshl_b32 s26, s30, 2
	s_andn2_b64 vcc, exec, s[20:21]
	s_waitcnt vmcnt(0) lgkmcnt(0)
	v_fma_f32 v74, v107, v74, v33
	v_fmac_f32_e32 v74, v105, v75
	v_fma_f32 v75, v107, v75, v33
	v_fmac_f32_e32 v74, v104, v86
	v_fmac_f32_e32 v75, v105, v86
	v_fma_f32 v83, v107, v86, v33
	v_fmac_f32_e32 v74, v101, v87
	v_fmac_f32_e32 v75, v104, v87
	v_fmac_f32_e32 v83, v105, v87
	v_fma_f32 v84, v107, v87, v33
	ds_read2st64_b32 v[86:87], v40 offset0:8 offset1:10
	v_fma_f32 v106, v107, v108, v33
	v_fmac_f32_e32 v106, v105, v109
	s_waitcnt lgkmcnt(0)
; __device__ __forceinline__ void conv_phase(LAS unsigned char* lds, const bf16_t* P, const float* cw, const float* cb, const float* ng, const float* nb, bf16_t* CAT, int bid, int G, const int tid) {
;     ...
; #pragma unroll
;             for (int i = 0; i < 46; ++i) {
;                 const float z = zs[(tb * 16 + i) * 128 + c];
; #pragma unroll
;                 for (int o = 0; o < 16; ++o) { const int j = i - o; if (j >= 0 && j <= 30) acc[o] += wj[j] * z; }
;             }
	v_fmac_f32_e32 v74, v100, v86
	v_fmac_f32_e32 v75, v101, v86
	v_fmac_f32_e32 v83, v104, v86
	v_fmac_f32_e32 v84, v105, v86
	v_fma_f32 v86, v107, v86, v33
	v_fmac_f32_e32 v74, v97, v87
	v_fmac_f32_e32 v75, v100, v87
	v_fmac_f32_e32 v83, v101, v87
	v_fmac_f32_e32 v84, v104, v87
	v_fmac_f32_e32 v86, v105, v87
	v_fma_f32 v87, v107, v87, v33
	v_fmac_f32_e32 v74, v96, v90
	v_fmac_f32_e32 v75, v97, v90
	v_fmac_f32_e32 v83, v100, v90
	v_fmac_f32_e32 v84, v101, v90
	v_fmac_f32_e32 v86, v104, v90
	v_fmac_f32_e32 v87, v105, v90
	v_fma_f32 v90, v107, v90, v33
	v_fmac_f32_e32 v74, v93, v91
	v_fmac_f32_e32 v75, v96, v91
	v_fmac_f32_e32 v83, v97, v91
	v_fmac_f32_e32 v84, v100, v91
	v_fmac_f32_e32 v86, v101, v91
	v_fmac_f32_e32 v87, v104, v91
	v_fmac_f32_e32 v90, v105, v91
	v_fma_f32 v91, v107, v91, v33
	v_fmac_f32_e32 v74, v92, v94
	v_fmac_f32_e32 v75, v93, v94
	v_fmac_f32_e32 v83, v96, v94
	v_fmac_f32_e32 v84, v97, v94
	v_fmac_f32_e32 v86, v100, v94
	v_fmac_f32_e32 v87, v101, v94
	v_fmac_f32_e32 v90, v104, v94
	v_fmac_f32_e32 v91, v105, v94
	v_fma_f32 v94, v107, v94, v33
	v_fmac_f32_e32 v74, v89, v95
	v_fmac_f32_e32 v75, v92, v95
	v_fmac_f32_e32 v83, v93, v95
	v_fmac_f32_e32 v84, v96, v95
	v_fmac_f32_e32 v86, v97, v95
	v_fmac_f32_e32 v87, v100, v95
	v_fmac_f32_e32 v90, v101, v95
	v_fmac_f32_e32 v91, v104, v95
	v_fmac_f32_e32 v94, v105, v95
	v_fma_f32 v95, v107, v95, v33
	v_fmac_f32_e32 v74, v88, v98
	v_fmac_f32_e32 v75, v89, v98
	v_fmac_f32_e32 v83, v92, v98
	v_fmac_f32_e32 v84, v93, v98
	v_fmac_f32_e32 v86, v96, v98
	v_fmac_f32_e32 v87, v97, v98
	v_fmac_f32_e32 v90, v100, v98
	v_fmac_f32_e32 v91, v101, v98
	v_fmac_f32_e32 v94, v104, v98
	v_fmac_f32_e32 v95, v105, v98
	v_fma_f32 v98, v107, v98, v33
	v_fmac_f32_e32 v74, v85, v99
	v_fmac_f32_e32 v75, v88, v99
	v_fmac_f32_e32 v83, v89, v99
	v_fmac_f32_e32 v84, v92, v99
	v_fmac_f32_e32 v86, v93, v99
	v_fmac_f32_e32 v87, v96, v99
	v_fmac_f32_e32 v90, v97, v99
	v_fmac_f32_e32 v91, v100, v99
	v_fmac_f32_e32 v94, v101, v99
	v_fmac_f32_e32 v95, v104, v99
	v_fmac_f32_e32 v98, v105, v99
	v_fma_f32 v99, v107, v99, v33
	v_fmac_f32_e32 v74, v82, v102
	v_fmac_f32_e32 v75, v85, v102
	v_fmac_f32_e32 v83, v88, v102
	v_fmac_f32_e32 v84, v89, v102
	v_fmac_f32_e32 v86, v92, v102
	v_fmac_f32_e32 v87, v93, v102
	v_fmac_f32_e32 v90, v96, v102
	v_fmac_f32_e32 v91, v97, v102
	v_fmac_f32_e32 v94, v100, v102
	v_fmac_f32_e32 v95, v101, v102
	v_fmac_f32_e32 v98, v104, v102
	v_fmac_f32_e32 v99, v105, v102
	v_fma_f32 v102, v107, v102, v33
	v_fmac_f32_e32 v74, v81, v103
	v_fmac_f32_e32 v75, v82, v103
	v_fmac_f32_e32 v83, v85, v103
	v_fmac_f32_e32 v84, v88, v103
	v_fmac_f32_e32 v86, v89, v103
	v_fmac_f32_e32 v87, v92, v103
	v_fmac_f32_e32 v90, v93, v103
	v_fmac_f32_e32 v91, v96, v103
	v_fmac_f32_e32 v94, v97, v103
	v_fmac_f32_e32 v95, v100, v103
	v_fmac_f32_e32 v98, v101, v103
	v_fmac_f32_e32 v99, v104, v103
	v_fmac_f32_e32 v102, v105, v103
	v_fma_f32 v103, v107, v103, v33
	v_fmac_f32_e32 v74, v80, v108
	v_fmac_f32_e32 v75, v81, v108
	v_fmac_f32_e32 v83, v82, v108
	v_fmac_f32_e32 v84, v85, v108
	v_fmac_f32_e32 v86, v88, v108
	v_fmac_f32_e32 v87, v89, v108
	v_fmac_f32_e32 v90, v92, v108
	v_fmac_f32_e32 v91, v93, v108
	v_fmac_f32_e32 v94, v96, v108
	v_fmac_f32_e32 v95, v97, v108
	v_fmac_f32_e32 v98, v100, v108
	v_fmac_f32_e32 v99, v101, v108
	v_fmac_f32_e32 v102, v104, v108
	v_fmac_f32_e32 v103, v105, v108
	v_fmac_f32_e32 v74, v79, v109
	v_fmac_f32_e32 v75, v80, v109
	v_fmac_f32_e32 v83, v81, v109
	v_fmac_f32_e32 v84, v82, v109
	v_fmac_f32_e32 v86, v85, v109
	v_fmac_f32_e32 v87, v88, v109
	v_fmac_f32_e32 v90, v89, v109
	v_fmac_f32_e32 v91, v92, v109
	v_fmac_f32_e32 v94, v93, v109
	v_fmac_f32_e32 v95, v96, v109
	v_fmac_f32_e32 v98, v97, v109
	v_fmac_f32_e32 v99, v100, v109
	v_fmac_f32_e32 v102, v101, v109
	v_fmac_f32_e32 v103, v104, v109
	v_fmac_f32_e32 v33, v107, v109
	ds_read2st64_b32 v[108:109], v40 offset0:32 offset1:34
	s_waitcnt lgkmcnt(0)
	v_fmac_f32_e32 v33, v105, v108
	v_fmac_f32_e32 v106, v104, v108
	v_fmac_f32_e32 v33, v104, v109
	ds_read2st64_b32 v[104:105], v40 offset0:36 offset1:38
	v_fmac_f32_e32 v103, v101, v108
	v_fmac_f32_e32 v106, v101, v109
	v_fmac_f32_e32 v102, v100, v108
	v_fmac_f32_e32 v103, v100, v109
	s_waitcnt lgkmcnt(0)
	v_fmac_f32_e32 v33, v101, v104
	v_fmac_f32_e32 v106, v100, v104
	v_fmac_f32_e32 v33, v100, v105
	ds_read2st64_b32 v[100:101], v40 offset0:40 offset1:42
	v_fmac_f32_e32 v99, v97, v108
	v_fmac_f32_e32 v102, v97, v109
	v_fmac_f32_e32 v103, v97, v104
	v_fmac_f32_e32 v106, v97, v105
	s_waitcnt lgkmcnt(0)
	v_fmac_f32_e32 v33, v97, v100
	v_fmac_f32_e32 v98, v96, v108
	v_fmac_f32_e32 v99, v96, v109
	v_fmac_f32_e32 v102, v96, v104
	v_fmac_f32_e32 v103, v96, v105
	v_fmac_f32_e32 v106, v96, v100
	v_fmac_f32_e32 v33, v96, v101
	ds_read2st64_b32 v[96:97], v40 offset0:44 offset1:46
	v_fmac_f32_e32 v95, v93, v108
	v_fmac_f32_e32 v98, v93, v109
	v_fmac_f32_e32 v99, v93, v104
	v_fmac_f32_e32 v102, v93, v105
	v_fmac_f32_e32 v103, v93, v100
	v_fmac_f32_e32 v106, v93, v101
	s_waitcnt lgkmcnt(0)
; __device__ __forceinline__ void conv_phase(LAS unsigned char* lds, const bf16_t* P, const float* cw, const float* cb, const float* ng, const float* nb, bf16_t* CAT, int bid, int G, const int tid) {
;     ...
; #pragma unroll
;             for (int i = 0; i < 46; ++i) {
;                 const float z = zs[(tb * 16 + i) * 128 + c];
; #pragma unroll
;                 for (int o = 0; o < 16; ++o) { const int j = i - o; if (j >= 0 && j <= 30) acc[o] += wj[j] * z; }
;             }
	v_fmac_f32_e32 v33, v93, v96
	v_fmac_f32_e32 v94, v92, v108
	v_fmac_f32_e32 v95, v92, v109
	v_fmac_f32_e32 v98, v92, v104
	v_fmac_f32_e32 v99, v92, v105
	v_fmac_f32_e32 v102, v92, v100
	v_fmac_f32_e32 v103, v92, v101
	v_fmac_f32_e32 v106, v92, v96
	v_fmac_f32_e32 v33, v92, v97
	ds_read2st64_b32 v[92:93], v40 offset0:48 offset1:50
	v_fmac_f32_e32 v74, v78, v108
	v_fmac_f32_e32 v75, v79, v108
	v_fmac_f32_e32 v83, v80, v108
	v_fmac_f32_e32 v84, v81, v108
	v_fmac_f32_e32 v86, v82, v108
	v_fmac_f32_e32 v87, v85, v108
	v_fmac_f32_e32 v90, v88, v108
	v_fmac_f32_e32 v91, v89, v108
	v_fmac_f32_e32 v74, v77, v109
	v_fmac_f32_e32 v75, v78, v109
	v_fmac_f32_e32 v83, v79, v109
	v_fmac_f32_e32 v84, v80, v109
	v_fmac_f32_e32 v86, v81, v109
	v_fmac_f32_e32 v87, v82, v109
	v_fmac_f32_e32 v90, v85, v109
	v_fmac_f32_e32 v91, v88, v109
	v_fmac_f32_e32 v94, v89, v109
	v_fmac_f32_e32 v74, v76, v104
	v_fmac_f32_e32 v75, v77, v104
	v_fmac_f32_e32 v83, v78, v104
	v_fmac_f32_e32 v84, v79, v104
	v_fmac_f32_e32 v86, v80, v104
	v_fmac_f32_e32 v87, v81, v104
	v_fmac_f32_e32 v90, v82, v104
	v_fmac_f32_e32 v91, v85, v104
	v_fmac_f32_e32 v94, v88, v104
	v_fmac_f32_e32 v95, v89, v104
	v_fmac_f32_e32 v74, v73, v105
	v_fmac_f32_e32 v75, v76, v105
	v_fmac_f32_e32 v83, v77, v105
	v_fmac_f32_e32 v84, v78, v105
	v_fmac_f32_e32 v86, v79, v105
	v_fmac_f32_e32 v87, v80, v105
	v_fmac_f32_e32 v90, v81, v105
	v_fmac_f32_e32 v91, v82, v105
	v_fmac_f32_e32 v94, v85, v105
	v_fmac_f32_e32 v95, v88, v105
	v_fmac_f32_e32 v98, v89, v105
	v_fmac_f32_e32 v74, v72, v100
	v_fmac_f32_e32 v75, v73, v100
	v_fmac_f32_e32 v83, v76, v100
	v_fmac_f32_e32 v84, v77, v100
	v_fmac_f32_e32 v86, v78, v100
	v_fmac_f32_e32 v87, v79, v100
	v_fmac_f32_e32 v90, v80, v100
	v_fmac_f32_e32 v91, v81, v100
	v_fmac_f32_e32 v94, v82, v100
	v_fmac_f32_e32 v95, v85, v100
	v_fmac_f32_e32 v98, v88, v100
	v_fmac_f32_e32 v99, v89, v100
	v_fmac_f32_e32 v102, v89, v101
	v_fmac_f32_e32 v103, v89, v96
	v_fmac_f32_e32 v106, v89, v97
	s_waitcnt lgkmcnt(0)
	v_fmac_f32_e32 v33, v89, v92
	v_fmac_f32_e32 v74, v71, v101
	v_fmac_f32_e32 v75, v72, v101
	v_fmac_f32_e32 v83, v73, v101
	v_fmac_f32_e32 v84, v76, v101
	v_fmac_f32_e32 v86, v77, v101
	v_fmac_f32_e32 v87, v78, v101
	v_fmac_f32_e32 v90, v79, v101
	v_fmac_f32_e32 v91, v80, v101
	v_fmac_f32_e32 v94, v81, v101
	v_fmac_f32_e32 v95, v82, v101
	v_fmac_f32_e32 v98, v85, v101
	v_fmac_f32_e32 v99, v88, v101
	v_fmac_f32_e32 v102, v88, v96
	v_fmac_f32_e32 v103, v88, v97
	v_fmac_f32_e32 v106, v88, v92
	v_fmac_f32_e32 v33, v88, v93
	ds_read2st64_b32 v[88:89], v40 offset0:52 offset1:54
	v_fmac_f32_e32 v74, v70, v96
	v_fmac_f32_e32 v75, v71, v96
	v_fmac_f32_e32 v83, v72, v96
	v_fmac_f32_e32 v84, v73, v96
	v_fmac_f32_e32 v86, v76, v96
	v_fmac_f32_e32 v87, v77, v96
	v_fmac_f32_e32 v90, v78, v96
	v_fmac_f32_e32 v91, v79, v96
	v_fmac_f32_e32 v94, v80, v96
	v_fmac_f32_e32 v95, v81, v96
	v_fmac_f32_e32 v98, v82, v96
	v_fmac_f32_e32 v99, v85, v96
	v_fmac_f32_e32 v74, v69, v97
	v_fmac_f32_e32 v75, v70, v97
	v_fmac_f32_e32 v83, v71, v97
	v_fmac_f32_e32 v84, v72, v97
	v_fmac_f32_e32 v86, v73, v97
	v_fmac_f32_e32 v87, v76, v97
	v_fmac_f32_e32 v90, v77, v97
	v_fmac_f32_e32 v91, v78, v97
	v_fmac_f32_e32 v94, v79, v97
	v_fmac_f32_e32 v95, v80, v97
	v_fmac_f32_e32 v98, v81, v97
	v_fmac_f32_e32 v99, v82, v97
	v_fmac_f32_e32 v102, v85, v97
	v_fmac_f32_e32 v74, v68, v92
	v_fmac_f32_e32 v75, v69, v92
	v_fmac_f32_e32 v83, v70, v92
	v_fmac_f32_e32 v84, v71, v92
	v_fmac_f32_e32 v86, v72, v92
	v_fmac_f32_e32 v87, v73, v92
	v_fmac_f32_e32 v90, v76, v92
	v_fmac_f32_e32 v91, v77, v92
	v_fmac_f32_e32 v94, v78, v92
	v_fmac_f32_e32 v95, v79, v92
	v_fmac_f32_e32 v98, v80, v92
	v_fmac_f32_e32 v99, v81, v92
	v_fmac_f32_e32 v102, v82, v92
	v_fmac_f32_e32 v103, v85, v92
	v_fmac_f32_e32 v74, v67, v93
	v_fmac_f32_e32 v75, v68, v93
	v_fmac_f32_e32 v83, v69, v93
	v_fmac_f32_e32 v84, v70, v93
	v_fmac_f32_e32 v86, v71, v93
	v_fmac_f32_e32 v87, v72, v93
	v_fmac_f32_e32 v90, v73, v93
	v_fmac_f32_e32 v91, v76, v93
	v_fmac_f32_e32 v94, v77, v93
	v_fmac_f32_e32 v95, v78, v93
	v_fmac_f32_e32 v98, v79, v93
	v_fmac_f32_e32 v99, v80, v93
	v_fmac_f32_e32 v102, v81, v93
	v_fmac_f32_e32 v103, v82, v93
	v_fmac_f32_e32 v106, v85, v93
	s_waitcnt lgkmcnt(0)
	v_fmac_f32_e32 v74, v66, v88
	v_fmac_f32_e32 v75, v67, v88
	v_fmac_f32_e32 v83, v68, v88
	v_fmac_f32_e32 v84, v69, v88
	v_fmac_f32_e32 v86, v70, v88
	v_fmac_f32_e32 v87, v71, v88
	v_fmac_f32_e32 v90, v72, v88
	v_fmac_f32_e32 v91, v73, v88
	v_fmac_f32_e32 v94, v76, v88
	v_fmac_f32_e32 v95, v77, v88
	v_fmac_f32_e32 v98, v78, v88
	v_fmac_f32_e32 v99, v79, v88
	v_fmac_f32_e32 v102, v80, v88
	v_fmac_f32_e32 v103, v81, v88
	v_fmac_f32_e32 v106, v82, v88
	v_fmac_f32_e32 v33, v85, v88
	v_fmac_f32_e32 v74, v34, v89
	v_fmac_f32_e32 v75, v66, v89
	v_fmac_f32_e32 v83, v67, v89
	v_fmac_f32_e32 v84, v68, v89
	v_fmac_f32_e32 v86, v69, v89
	v_fmac_f32_e32 v87, v70, v89
	v_fmac_f32_e32 v90, v71, v89
	v_fmac_f32_e32 v91, v72, v89
	v_fmac_f32_e32 v94, v73, v89
	v_fmac_f32_e32 v95, v76, v89
	v_fmac_f32_e32 v98, v77, v89
	v_fmac_f32_e32 v99, v78, v89
	v_fmac_f32_e32 v102, v79, v89
	v_fmac_f32_e32 v103, v80, v89
	v_fmac_f32_e32 v106, v81, v89
	v_fmac_f32_e32 v33, v82, v89
	ds_read2st64_b32 v[88:89], v40 offset0:56 offset1:58
	s_waitcnt lgkmcnt(0)
	v_fmac_f32_e32 v33, v81, v88
	v_fmac_f32_e32 v106, v80, v88
	v_fmac_f32_e32 v33, v80, v89
	ds_read2st64_b32 v[80:81], v40 offset0:60 offset1:62
	v_fmac_f32_e32 v103, v79, v88
	v_fmac_f32_e32 v106, v79, v89
	v_fmac_f32_e32 v102, v78, v88
	v_fmac_f32_e32 v103, v78, v89
	s_waitcnt lgkmcnt(0)
; __device__ __forceinline__ void conv_phase(LAS unsigned char* lds, const bf16_t* P, const float* cw, const float* cb, const float* ng, const float* nb, bf16_t* CAT, int bid, int G, const int tid) {
;     ...
; #pragma unroll
;             for (int i = 0; i < 46; ++i) {
;                 const float z = zs[(tb * 16 + i) * 128 + c];
; #pragma unroll
;                 for (int o = 0; o < 16; ++o) { const int j = i - o; if (j >= 0 && j <= 30) acc[o] += wj[j] * z; }
;             }
; #pragma unroll
;             for (int o = 0; o < 16; ++o) co[(tb * 16 + o) * 128 + c] = acc[o];
;         }
;         __syncthreads();
	v_fmac_f32_e32 v33, v79, v80
	v_fmac_f32_e32 v106, v78, v80
	v_fmac_f32_e32 v33, v78, v81
	ds_read2st64_b32 v[78:79], v40 offset0:64 offset1:66
	v_fmac_f32_e32 v99, v77, v88
	v_fmac_f32_e32 v102, v77, v89
	v_fmac_f32_e32 v103, v77, v80
	v_fmac_f32_e32 v106, v77, v81
	s_waitcnt lgkmcnt(0)
	v_fmac_f32_e32 v33, v77, v78
	v_fmac_f32_e32 v98, v76, v88
	v_fmac_f32_e32 v99, v76, v89
	v_fmac_f32_e32 v102, v76, v80
	v_fmac_f32_e32 v103, v76, v81
	v_fmac_f32_e32 v106, v76, v78
	v_fmac_f32_e32 v33, v76, v79
	ds_read2st64_b32 v[76:77], v40 offset0:68 offset1:70
	v_fmac_f32_e32 v95, v73, v88
	v_fmac_f32_e32 v98, v73, v89
	v_fmac_f32_e32 v99, v73, v80
	v_fmac_f32_e32 v102, v73, v81
	v_fmac_f32_e32 v103, v73, v78
	v_fmac_f32_e32 v106, v73, v79
	s_waitcnt lgkmcnt(0)
	v_fmac_f32_e32 v33, v73, v76
	v_fmac_f32_e32 v94, v72, v88
	v_fmac_f32_e32 v95, v72, v89
	v_fmac_f32_e32 v98, v72, v80
	v_fmac_f32_e32 v99, v72, v81
	v_fmac_f32_e32 v102, v72, v78
	v_fmac_f32_e32 v103, v72, v79
	v_fmac_f32_e32 v106, v72, v76
	v_fmac_f32_e32 v33, v72, v77
	ds_read2st64_b32 v[72:73], v40 offset0:72 offset1:74
	v_fmac_f32_e32 v91, v71, v88
	v_fmac_f32_e32 v94, v71, v89
	v_fmac_f32_e32 v95, v71, v80
	v_fmac_f32_e32 v98, v71, v81
	v_fmac_f32_e32 v99, v71, v78
	v_fmac_f32_e32 v102, v71, v79
	v_fmac_f32_e32 v103, v71, v76
	v_fmac_f32_e32 v106, v71, v77
	s_waitcnt lgkmcnt(0)
	v_fmac_f32_e32 v33, v71, v72
	v_fmac_f32_e32 v90, v70, v88
	v_fmac_f32_e32 v91, v70, v89
	v_fmac_f32_e32 v94, v70, v80
	v_fmac_f32_e32 v95, v70, v81
	v_fmac_f32_e32 v98, v70, v78
	v_fmac_f32_e32 v99, v70, v79
	v_fmac_f32_e32 v102, v70, v76
	v_fmac_f32_e32 v103, v70, v77
	v_fmac_f32_e32 v106, v70, v72
	v_fmac_f32_e32 v33, v70, v73
	ds_read2st64_b32 v[70:71], v40 offset0:76 offset1:78
	v_fmac_f32_e32 v87, v69, v88
	v_fmac_f32_e32 v90, v69, v89
	v_fmac_f32_e32 v91, v69, v80
	v_fmac_f32_e32 v94, v69, v81
	v_fmac_f32_e32 v95, v69, v78
	v_fmac_f32_e32 v98, v69, v79
	v_fmac_f32_e32 v99, v69, v76
	v_fmac_f32_e32 v102, v69, v77
	v_fmac_f32_e32 v103, v69, v72
	v_fmac_f32_e32 v106, v69, v73
	s_waitcnt lgkmcnt(0)
	v_fmac_f32_e32 v33, v69, v70
	v_fmac_f32_e32 v86, v68, v88
	v_fmac_f32_e32 v87, v68, v89
	v_fmac_f32_e32 v90, v68, v80
	v_fmac_f32_e32 v91, v68, v81
	v_fmac_f32_e32 v94, v68, v78
	v_fmac_f32_e32 v95, v68, v79
	v_fmac_f32_e32 v98, v68, v76
	v_fmac_f32_e32 v99, v68, v77
	v_fmac_f32_e32 v102, v68, v72
	v_fmac_f32_e32 v103, v68, v73
	v_fmac_f32_e32 v106, v68, v70
	v_fmac_f32_e32 v33, v68, v71
	ds_read2st64_b32 v[68:69], v40 offset0:80 offset1:82
	v_fmac_f32_e32 v84, v67, v88
	v_fmac_f32_e32 v86, v67, v89
	v_fmac_f32_e32 v87, v67, v80
	v_fmac_f32_e32 v90, v67, v81
	v_fmac_f32_e32 v91, v67, v78
	v_fmac_f32_e32 v94, v67, v79
	v_fmac_f32_e32 v95, v67, v76
	v_fmac_f32_e32 v98, v67, v77
	v_fmac_f32_e32 v99, v67, v72
	v_fmac_f32_e32 v102, v67, v73
	v_fmac_f32_e32 v103, v67, v70
	v_fmac_f32_e32 v106, v67, v71
	s_waitcnt lgkmcnt(0)
	v_fmac_f32_e32 v33, v67, v68
	v_fmac_f32_e32 v83, v66, v88
	v_fmac_f32_e32 v84, v66, v89
	v_fmac_f32_e32 v86, v66, v80
	v_fmac_f32_e32 v87, v66, v81
	v_fmac_f32_e32 v90, v66, v78
	v_fmac_f32_e32 v91, v66, v79
	v_fmac_f32_e32 v94, v66, v76
	v_fmac_f32_e32 v95, v66, v77
	v_fmac_f32_e32 v98, v66, v72
	v_fmac_f32_e32 v99, v66, v73
	v_fmac_f32_e32 v102, v66, v70
	v_fmac_f32_e32 v103, v66, v71
	v_fmac_f32_e32 v106, v66, v68
	v_fmac_f32_e32 v33, v66, v69
	ds_read2st64_b32 v[66:67], v40 offset0:84 offset1:86
	v_fmac_f32_e32 v75, v34, v88
	v_fmac_f32_e32 v83, v34, v89
	v_fmac_f32_e32 v84, v34, v80
	v_fmac_f32_e32 v86, v34, v81
	v_fmac_f32_e32 v87, v34, v78
	v_fmac_f32_e32 v90, v34, v79
	v_fmac_f32_e32 v91, v34, v76
	v_fmac_f32_e32 v94, v34, v77
	v_fmac_f32_e32 v95, v34, v72
	v_fmac_f32_e32 v98, v34, v73
	v_fmac_f32_e32 v99, v34, v70
	v_fmac_f32_e32 v102, v34, v71
	v_fmac_f32_e32 v103, v34, v68
	v_fmac_f32_e32 v106, v34, v69
	s_waitcnt lgkmcnt(0)
	v_fmac_f32_e32 v33, v34, v66
	v_fmac_f32_e32 v74, v35, v88
	v_fmac_f32_e32 v75, v35, v89
	v_fmac_f32_e32 v83, v35, v80
	v_fmac_f32_e32 v84, v35, v81
	v_fmac_f32_e32 v86, v35, v78
	v_fmac_f32_e32 v87, v35, v79
	v_fmac_f32_e32 v90, v35, v76
	v_fmac_f32_e32 v91, v35, v77
	v_fmac_f32_e32 v94, v35, v72
	v_fmac_f32_e32 v95, v35, v73
	v_fmac_f32_e32 v98, v35, v70
	v_fmac_f32_e32 v99, v35, v71
	v_fmac_f32_e32 v102, v35, v68
	v_fmac_f32_e32 v103, v35, v69
	v_fmac_f32_e32 v106, v35, v66
	v_fmac_f32_e32 v33, v35, v67
	ds_read2st64_b32 v[34:35], v40 offset0:88 offset1:90
	v_fmac_f32_e32 v74, v31, v89
	v_fmac_f32_e32 v75, v31, v80
	v_fmac_f32_e32 v74, v32, v80
	v_fmac_f32_e32 v75, v32, v81
	v_fmac_f32_e32 v83, v31, v81
	v_fmac_f32_e32 v84, v31, v78
	v_fmac_f32_e32 v86, v31, v79
	v_fmac_f32_e32 v87, v31, v76
	v_fmac_f32_e32 v90, v31, v77
	v_fmac_f32_e32 v91, v31, v72
	v_fmac_f32_e32 v94, v31, v73
	v_fmac_f32_e32 v95, v31, v70
	v_fmac_f32_e32 v98, v31, v71
	v_fmac_f32_e32 v99, v31, v68
	v_fmac_f32_e32 v102, v31, v69
	v_fmac_f32_e32 v103, v31, v66
	v_fmac_f32_e32 v106, v31, v67
	s_waitcnt lgkmcnt(0)
	v_fmac_f32_e32 v33, v31, v34
	v_fmac_f32_e32 v83, v32, v78
	v_fmac_f32_e32 v84, v32, v79
	v_fmac_f32_e32 v86, v32, v76
	v_fmac_f32_e32 v87, v32, v77
	v_fmac_f32_e32 v90, v32, v72
	v_fmac_f32_e32 v91, v32, v73
	v_fmac_f32_e32 v94, v32, v70
	v_fmac_f32_e32 v95, v32, v71
	v_fmac_f32_e32 v98, v32, v68
	v_fmac_f32_e32 v99, v32, v69
	v_fmac_f32_e32 v102, v32, v66
	v_fmac_f32_e32 v103, v32, v67
	v_fmac_f32_e32 v106, v32, v34
	v_fmac_f32_e32 v33, v32, v35
	ds_write2st64_b32 v40, v74, v75 offset0:188 offset1:190
	ds_write2st64_b32 v40, v83, v84 offset0:192 offset1:194
	ds_write2st64_b32 v40, v86, v87 offset0:196 offset1:198
	ds_write2st64_b32 v40, v90, v91 offset0:200 offset1:202
	ds_write2st64_b32 v40, v94, v95 offset0:204 offset1:206
	ds_write2st64_b32 v40, v98, v99 offset0:208 offset1:210
	ds_write2st64_b32 v40, v102, v103 offset0:212 offset1:214
	ds_write2st64_b32 v40, v106, v33 offset0:216 offset1:218
	s_waitcnt lgkmcnt(0)
	s_barrier
; #define LAS __attribute__((address_space(3)))
; __device__ __forceinline__ void conv_phase(LAS unsigned char* lds, const bf16_t* P, const float* cw, const float* cb, const float* ng, const float* nb, bf16_t* CAT, int bid, int G, const int tid) {
;     ...
;             const f32x2 gg = *(const f32x2*)(ng + g * 128 + 2 * lane), bb = *(const f32x2*)(nb + g * 128 + 2 * lane);
; #pragma unroll
;             for (int k = 0; k < 8; ++k) {
;                 const int tok = w * 8 + k;
;                 const f32x2 v = *(const LAS f32x2*)(co + tok * 128 + 2 * lane);
;                 const float mean = wave_sum(v[0] + v[1]) * (1.0f / 128.0f);
	v_lshl_add_u64 v[32:33], v[26:27], 0, s[26:27]
	global_load_dwordx2 v[34:35], v[32:33], off
	v_lshl_add_u64 v[32:33], v[28:29], 0, s[26:27]
	global_load_dwordx2 v[32:33], v[32:33], off
	s_lshl_b32 s26, s30, 1
	v_mov_b32_e32 v31, v177
	ds_read_b64 v[110:111], v58 offset:48128
	ds_read_b64 v[112:113], v59 offset:48128
	ds_read_b64 v[114:115], v60 offset:48128
	ds_read_b64 v[116:117], v61 offset:48128
	ds_read_b64 v[118:119], v62 offset:48128
	ds_read_b64 v[120:121], v63 offset:48128
	ds_read_b64 v[122:123], v64 offset:48128
	ds_read_b64 v[124:125], v65 offset:48128
	s_waitcnt lgkmcnt(7)
	v_add_f32_e32 v126, v110, v111
	s_waitcnt lgkmcnt(6)
	v_add_f32_e32 v127, v112, v113
	s_waitcnt lgkmcnt(5)
	v_add_f32_e32 v128, v114, v115
	s_waitcnt lgkmcnt(4)
	v_add_f32_e32 v129, v116, v117
	s_waitcnt lgkmcnt(3)
	v_add_f32_e32 v130, v118, v119
	s_waitcnt lgkmcnt(2)
	v_add_f32_e32 v131, v120, v121
	s_waitcnt lgkmcnt(1)
	v_add_f32_e32 v132, v122, v123
	s_waitcnt lgkmcnt(0)
	v_add_f32_e32 v133, v124, v125
	ds_bpermute_b32 v134, v42, v126
	ds_bpermute_b32 v135, v42, v127
	ds_bpermute_b32 v136, v42, v128
	ds_bpermute_b32 v137, v42, v129
	ds_bpermute_b32 v138, v42, v130
	ds_bpermute_b32 v139, v42, v131
	ds_bpermute_b32 v140, v42, v132
	ds_bpermute_b32 v141, v42, v133
	s_waitcnt lgkmcnt(7)
	v_add_f32_e32 v126, v126, v134
	s_waitcnt lgkmcnt(6)
	v_add_f32_e32 v127, v127, v135
	s_waitcnt lgkmcnt(5)
	v_add_f32_e32 v128, v128, v136
	s_waitcnt lgkmcnt(4)
	v_add_f32_e32 v129, v129, v137
	s_waitcnt lgkmcnt(3)
	v_add_f32_e32 v130, v130, v138
	s_waitcnt lgkmcnt(2)
	v_add_f32_e32 v131, v131, v139
	s_waitcnt lgkmcnt(1)
	v_add_f32_e32 v132, v132, v140
	s_waitcnt lgkmcnt(0)
	v_add_f32_e32 v133, v133, v141
	ds_bpermute_b32 v134, v43, v126
	ds_bpermute_b32 v135, v43, v127
	ds_bpermute_b32 v136, v43, v128
	ds_bpermute_b32 v137, v43, v129
	ds_bpermute_b32 v138, v43, v130
	ds_bpermute_b32 v139, v43, v131
	ds_bpermute_b32 v140, v43, v132
	ds_bpermute_b32 v141, v43, v133
	s_waitcnt lgkmcnt(7)
	v_add_f32_e32 v126, v126, v134
	s_waitcnt lgkmcnt(6)
	v_add_f32_e32 v127, v127, v135
	s_waitcnt lgkmcnt(5)
	v_add_f32_e32 v128, v128, v136
	s_waitcnt lgkmcnt(4)
	v_add_f32_e32 v129, v129, v137
	s_waitcnt lgkmcnt(3)
	v_add_f32_e32 v130, v130, v138
	s_waitcnt lgkmcnt(2)
	v_add_f32_e32 v131, v131, v139
	s_waitcnt lgkmcnt(1)
	v_add_f32_e32 v132, v132, v140
	s_waitcnt lgkmcnt(0)
	v_add_f32_e32 v133, v133, v141
	ds_bpermute_b32 v134, v44, v126
	ds_bpermute_b32 v135, v44, v127
	ds_bpermute_b32 v136, v44, v128
	ds_bpermute_b32 v137, v44, v129
	ds_bpermute_b32 v138, v44, v130
	ds_bpermute_b32 v139, v44, v131
	ds_bpermute_b32 v140, v44, v132
	ds_bpermute_b32 v141, v44, v133
	s_waitcnt lgkmcnt(7)
	v_add_f32_e32 v126, v126, v134
	s_waitcnt lgkmcnt(6)
	v_add_f32_e32 v127, v127, v135
	s_waitcnt lgkmcnt(5)
	v_add_f32_e32 v128, v128, v136
	s_waitcnt lgkmcnt(4)
	v_add_f32_e32 v129, v129, v137
	s_waitcnt lgkmcnt(3)
	v_add_f32_e32 v130, v130, v138
	s_waitcnt lgkmcnt(2)
	v_add_f32_e32 v131, v131, v139
	s_waitcnt lgkmcnt(1)
	v_add_f32_e32 v132, v132, v140
	s_waitcnt lgkmcnt(0)
	v_add_f32_e32 v133, v133, v141
	ds_bpermute_b32 v134, v45, v126
	ds_bpermute_b32 v135, v45, v127
	ds_bpermute_b32 v136, v45, v128
	ds_bpermute_b32 v137, v45, v129
	ds_bpermute_b32 v138, v45, v130
	ds_bpermute_b32 v139, v45, v131
	ds_bpermute_b32 v140, v45, v132
	ds_bpermute_b32 v141, v45, v133
	s_waitcnt lgkmcnt(7)
	v_add_f32_e32 v126, v126, v134
	s_waitcnt lgkmcnt(6)
	v_add_f32_e32 v127, v127, v135
	s_waitcnt lgkmcnt(5)
	v_add_f32_e32 v128, v128, v136
	s_waitcnt lgkmcnt(4)
	v_add_f32_e32 v129, v129, v137
	s_waitcnt lgkmcnt(3)
	v_add_f32_e32 v130, v130, v138
	s_waitcnt lgkmcnt(2)
	v_add_f32_e32 v131, v131, v139
	s_waitcnt lgkmcnt(1)
	v_add_f32_e32 v132, v132, v140
	s_waitcnt lgkmcnt(0)
	v_add_f32_e32 v133, v133, v141
	ds_bpermute_b32 v134, v46, v126
	ds_bpermute_b32 v135, v46, v127
	ds_bpermute_b32 v136, v46, v128
	ds_bpermute_b32 v137, v46, v129
	ds_bpermute_b32 v138, v46, v130
	ds_bpermute_b32 v139, v46, v131
	ds_bpermute_b32 v140, v46, v132
	ds_bpermute_b32 v141, v46, v133
	s_waitcnt lgkmcnt(7)
	v_add_f32_e32 v126, v126, v134
	s_waitcnt lgkmcnt(6)
	v_add_f32_e32 v127, v127, v135
	s_waitcnt lgkmcnt(5)
	v_add_f32_e32 v128, v128, v136
	s_waitcnt lgkmcnt(4)
	v_add_f32_e32 v129, v129, v137
	s_waitcnt lgkmcnt(3)
	v_add_f32_e32 v130, v130, v138
	s_waitcnt lgkmcnt(2)
	v_add_f32_e32 v131, v131, v139
	s_waitcnt lgkmcnt(1)
	v_add_f32_e32 v132, v132, v140
	s_waitcnt lgkmcnt(0)
	v_add_f32_e32 v133, v133, v141
	ds_bpermute_b32 v134, v47, v126
	ds_bpermute_b32 v135, v47, v127
	ds_bpermute_b32 v136, v47, v128
	ds_bpermute_b32 v137, v47, v129
	ds_bpermute_b32 v138, v47, v130
	ds_bpermute_b32 v139, v47, v131
	ds_bpermute_b32 v140, v47, v132
	ds_bpermute_b32 v141, v47, v133
	s_waitcnt lgkmcnt(7)
	v_add_f32_e32 v126, v126, v134
	s_waitcnt lgkmcnt(6)
	v_add_f32_e32 v127, v127, v135
	s_waitcnt lgkmcnt(5)
	v_add_f32_e32 v128, v128, v136
	s_waitcnt lgkmcnt(4)
	v_add_f32_e32 v129, v129, v137
	s_waitcnt lgkmcnt(3)
	v_add_f32_e32 v130, v130, v138
	s_waitcnt lgkmcnt(2)
	v_add_f32_e32 v131, v131, v139
	s_waitcnt lgkmcnt(1)
	v_add_f32_e32 v132, v132, v140
	s_waitcnt lgkmcnt(0)
; __device__ __forceinline__ void conv_phase(LAS unsigned char* lds, const bf16_t* P, const float* cw, const float* cb, const float* ng, const float* nb, bf16_t* CAT, int bid, int G, const int tid) {
;     ...
;                 const float mean = wave_sum(v[0] + v[1]) * (1.0f / 128.0f);
;                 const float d0 = v[0] - mean, d1 = v[1] - mean;
;                 const float rs = __builtin_amdgcn_rsqf(wave_sum(d0 * d0 + d1 * d1) * (1.0f / 128.0f) + EPS);
	v_add_f32_e32 v133, v133, v141
	v_fmac_f32_e32 v111, 0xbc000000, v126
	v_fmamk_f32 v110, v126, 0xbc000000, v110
	v_fmac_f32_e32 v113, 0xbc000000, v127
	v_fmamk_f32 v112, v127, 0xbc000000, v112
	v_fmac_f32_e32 v115, 0xbc000000, v128
	v_fmamk_f32 v114, v128, 0xbc000000, v114
	v_fmac_f32_e32 v117, 0xbc000000, v129
	v_fmamk_f32 v116, v129, 0xbc000000, v116
	v_fmac_f32_e32 v119, 0xbc000000, v130
	v_fmamk_f32 v118, v130, 0xbc000000, v118
	v_fmac_f32_e32 v121, 0xbc000000, v131
	v_fmamk_f32 v120, v131, 0xbc000000, v120
	v_fmac_f32_e32 v123, 0xbc000000, v132
	v_fmamk_f32 v122, v132, 0xbc000000, v122
	v_fmac_f32_e32 v125, 0xbc000000, v133
	v_fmamk_f32 v124, v133, 0xbc000000, v124
	v_mul_f32_e32 v126, v111, v111
	v_fmac_f32_e32 v126, v110, v110
	v_mul_f32_e32 v127, v113, v113
	v_fmac_f32_e32 v127, v112, v112
	v_mul_f32_e32 v128, v115, v115
	v_fmac_f32_e32 v128, v114, v114
	v_mul_f32_e32 v129, v117, v117
	v_fmac_f32_e32 v129, v116, v116
	v_mul_f32_e32 v130, v119, v119
	v_fmac_f32_e32 v130, v118, v118
	v_mul_f32_e32 v131, v121, v121
	v_fmac_f32_e32 v131, v120, v120
	v_mul_f32_e32 v132, v123, v123
	v_fmac_f32_e32 v132, v122, v122
	v_mul_f32_e32 v133, v125, v125
	v_fmac_f32_e32 v133, v124, v124
	ds_bpermute_b32 v134, v42, v126
	ds_bpermute_b32 v135, v42, v127
	ds_bpermute_b32 v136, v42, v128
	ds_bpermute_b32 v137, v42, v129
	ds_bpermute_b32 v138, v42, v130
	ds_bpermute_b32 v139, v42, v131
	ds_bpermute_b32 v140, v42, v132
	ds_bpermute_b32 v141, v42, v133
	s_waitcnt lgkmcnt(7)
	v_add_f32_e32 v126, v126, v134
	s_waitcnt lgkmcnt(6)
	v_add_f32_e32 v127, v127, v135
	s_waitcnt lgkmcnt(5)
	v_add_f32_e32 v128, v128, v136
	s_waitcnt lgkmcnt(4)
	v_add_f32_e32 v129, v129, v137
	s_waitcnt lgkmcnt(3)
	v_add_f32_e32 v130, v130, v138
	s_waitcnt lgkmcnt(2)
	v_add_f32_e32 v131, v131, v139
	s_waitcnt lgkmcnt(1)
	v_add_f32_e32 v132, v132, v140
	s_waitcnt lgkmcnt(0)
	v_add_f32_e32 v133, v133, v141
	ds_bpermute_b32 v134, v43, v126
	ds_bpermute_b32 v135, v43, v127
	ds_bpermute_b32 v136, v43, v128
	ds_bpermute_b32 v137, v43, v129
	ds_bpermute_b32 v138, v43, v130
	ds_bpermute_b32 v139, v43, v131
	ds_bpermute_b32 v140, v43, v132
	ds_bpermute_b32 v141, v43, v133
	s_waitcnt lgkmcnt(7)
	v_add_f32_e32 v126, v126, v134
	s_waitcnt lgkmcnt(6)
	v_add_f32_e32 v127, v127, v135
	s_waitcnt lgkmcnt(5)
	v_add_f32_e32 v128, v128, v136
	s_waitcnt lgkmcnt(4)
	v_add_f32_e32 v129, v129, v137
	s_waitcnt lgkmcnt(3)
	v_add_f32_e32 v130, v130, v138
	s_waitcnt lgkmcnt(2)
	v_add_f32_e32 v131, v131, v139
	s_waitcnt lgkmcnt(1)
	v_add_f32_e32 v132, v132, v140
	s_waitcnt lgkmcnt(0)
	v_add_f32_e32 v133, v133, v141
	ds_bpermute_b32 v134, v44, v126
	ds_bpermute_b32 v135, v44, v127
	ds_bpermute_b32 v136, v44, v128
	ds_bpermute_b32 v137, v44, v129
	ds_bpermute_b32 v138, v44, v130
	ds_bpermute_b32 v139, v44, v131
	ds_bpermute_b32 v140, v44, v132
	ds_bpermute_b32 v141, v44, v133
	s_waitcnt lgkmcnt(7)
	v_add_f32_e32 v126, v126, v134
	s_waitcnt lgkmcnt(6)
	v_add_f32_e32 v127, v127, v135
	s_waitcnt lgkmcnt(5)
	v_add_f32_e32 v128, v128, v136
	s_waitcnt lgkmcnt(4)
	v_add_f32_e32 v129, v129, v137
	s_waitcnt lgkmcnt(3)
	v_add_f32_e32 v130, v130, v138
	s_waitcnt lgkmcnt(2)
	v_add_f32_e32 v131, v131, v139
	s_waitcnt lgkmcnt(1)
	v_add_f32_e32 v132, v132, v140
	s_waitcnt lgkmcnt(0)
	v_add_f32_e32 v133, v133, v141
	ds_bpermute_b32 v134, v45, v126
	ds_bpermute_b32 v135, v45, v127
	ds_bpermute_b32 v136, v45, v128
	ds_bpermute_b32 v137, v45, v129
	ds_bpermute_b32 v138, v45, v130
	ds_bpermute_b32 v139, v45, v131
	ds_bpermute_b32 v140, v45, v132
	ds_bpermute_b32 v141, v45, v133
	s_waitcnt lgkmcnt(7)
	v_add_f32_e32 v126, v126, v134
	s_waitcnt lgkmcnt(6)
	v_add_f32_e32 v127, v127, v135
	s_waitcnt lgkmcnt(5)
	v_add_f32_e32 v128, v128, v136
	s_waitcnt lgkmcnt(4)
	v_add_f32_e32 v129, v129, v137
	s_waitcnt lgkmcnt(3)
	v_add_f32_e32 v130, v130, v138
	s_waitcnt lgkmcnt(2)
	v_add_f32_e32 v131, v131, v139
	s_waitcnt lgkmcnt(1)
	v_add_f32_e32 v132, v132, v140
	s_waitcnt lgkmcnt(0)
	v_add_f32_e32 v133, v133, v141
	ds_bpermute_b32 v134, v46, v126
	ds_bpermute_b32 v135, v46, v127
	ds_bpermute_b32 v136, v46, v128
	ds_bpermute_b32 v137, v46, v129
	ds_bpermute_b32 v138, v46, v130
	ds_bpermute_b32 v139, v46, v131
	ds_bpermute_b32 v140, v46, v132
	ds_bpermute_b32 v141, v46, v133
	s_waitcnt lgkmcnt(7)
	v_add_f32_e32 v126, v126, v134
	s_waitcnt lgkmcnt(6)
	v_add_f32_e32 v127, v127, v135
	s_waitcnt lgkmcnt(5)
	v_add_f32_e32 v128, v128, v136
	s_waitcnt lgkmcnt(4)
	v_add_f32_e32 v129, v129, v137
	s_waitcnt lgkmcnt(3)
	v_add_f32_e32 v130, v130, v138
	s_waitcnt lgkmcnt(2)
	v_add_f32_e32 v131, v131, v139
	s_waitcnt lgkmcnt(1)
	v_add_f32_e32 v132, v132, v140
	s_waitcnt lgkmcnt(0)
	v_add_f32_e32 v133, v133, v141
	ds_bpermute_b32 v134, v47, v126
	ds_bpermute_b32 v135, v47, v127
	ds_bpermute_b32 v136, v47, v128
	ds_bpermute_b32 v137, v47, v129
	ds_bpermute_b32 v138, v47, v130
	ds_bpermute_b32 v139, v47, v131
	ds_bpermute_b32 v140, v47, v132
	ds_bpermute_b32 v141, v47, v133
	s_waitcnt lgkmcnt(7)
	v_add_f32_e32 v126, v126, v134
	s_waitcnt lgkmcnt(6)
	v_add_f32_e32 v127, v127, v135
	s_waitcnt lgkmcnt(5)
	v_add_f32_e32 v128, v128, v136
	s_waitcnt lgkmcnt(4)
	v_add_f32_e32 v129, v129, v137
	s_waitcnt lgkmcnt(3)
	v_add_f32_e32 v130, v130, v138
	s_waitcnt lgkmcnt(2)
	v_add_f32_e32 v131, v131, v139
	s_waitcnt lgkmcnt(1)
	v_add_f32_e32 v132, v132, v140
	s_waitcnt lgkmcnt(0)
; __device__ __forceinline__ unsigned cvt_pk_bf16(float lo, float hi) { unsigned r; asm("v_cvt_pk_bf16_f32 %0, %1, %2" : "=v"(r) : "v"(lo), "v"(hi)); return r; }
; __device__ __forceinline__ float silu_f(float x) { return x * fast_sigmoid(x); }
; __device__ __forceinline__ void conv_phase(LAS unsigned char* lds, const bf16_t* P, const float* cw, const float* cb, const float* ng, const float* nb, bf16_t* CAT, int bid, int G, const int tid) {
;     ...
;                 const float rs = __builtin_amdgcn_rsqf(wave_sum(d0 * d0 + d1 * d1) * (1.0f / 128.0f) + EPS);
;                 const float y0 = d0 * rs * gg[0] + bb[0], y1 = d1 * rs * gg[1] + bb[1];
;                 *(unsigned*)(CAT + (size_t)(b * SEQ + t0 + tok) * D + 1024 + g * 128 + 2 * lane) = cvt_pk_bf16(silu_f(y0), silu_f(y1));
	v_add_f32_e32 v133, v133, v141
	v_fmamk_f32 v126, v126, 0x3c000000, v189
	v_fmamk_f32 v127, v127, 0x3c000000, v189
	v_fmamk_f32 v128, v128, 0x3c000000, v189
	v_fmamk_f32 v129, v129, 0x3c000000, v189
	v_fmamk_f32 v130, v130, 0x3c000000, v189
	v_fmamk_f32 v131, v131, 0x3c000000, v189
	v_fmamk_f32 v132, v132, 0x3c000000, v189
	v_fmamk_f32 v133, v133, 0x3c000000, v189
	v_rsq_f32_e32 v126, v126
	v_rsq_f32_e32 v127, v127
	v_rsq_f32_e32 v128, v128
	v_rsq_f32_e32 v129, v129
	v_rsq_f32_e32 v130, v130
	v_rsq_f32_e32 v131, v131
	v_rsq_f32_e32 v132, v132
	v_rsq_f32_e32 v133, v133
	s_waitcnt vmcnt(0)
	v_mul_f32_e32 v110, v110, v126
	v_mul_f32_e32 v111, v111, v126
	v_mul_f32_e32 v112, v112, v127
	v_mul_f32_e32 v113, v113, v127
	v_mul_f32_e32 v114, v114, v128
	v_mul_f32_e32 v115, v115, v128
	v_mul_f32_e32 v116, v116, v129
	v_mul_f32_e32 v117, v117, v129
	v_mul_f32_e32 v118, v118, v130
	v_mul_f32_e32 v119, v119, v130
	v_mul_f32_e32 v120, v120, v131
	v_mul_f32_e32 v121, v121, v131
	v_mul_f32_e32 v122, v122, v132
	v_mul_f32_e32 v123, v123, v132
	v_mul_f32_e32 v124, v124, v133
	v_mul_f32_e32 v125, v125, v133
	v_fma_f32 v110, v34, v110, v32
	v_fma_f32 v111, v35, v111, v33
	v_fma_f32 v112, v34, v112, v32
	v_fma_f32 v113, v35, v113, v33
	v_fma_f32 v114, v34, v114, v32
	v_fma_f32 v115, v35, v115, v33
	v_fma_f32 v116, v34, v116, v32
	v_fma_f32 v117, v35, v117, v33
	v_fma_f32 v118, v34, v118, v32
	v_fma_f32 v119, v35, v119, v33
	v_fma_f32 v120, v34, v120, v32
	v_fma_f32 v121, v35, v121, v33
	v_fma_f32 v122, v34, v122, v32
	v_fma_f32 v123, v35, v123, v33
	v_fma_f32 v124, v34, v124, v32
	v_fma_f32 v125, v35, v125, v33
	v_mul_f32_e32 v134, 0xbfb8aa3b, v110
	v_mul_f32_e32 v142, 0xbfb8aa3b, v111
	v_mul_f32_e32 v135, 0xbfb8aa3b, v112
	v_mul_f32_e32 v143, 0xbfb8aa3b, v113
	v_mul_f32_e32 v136, 0xbfb8aa3b, v114
	v_mul_f32_e32 v144, 0xbfb8aa3b, v115
	v_mul_f32_e32 v137, 0xbfb8aa3b, v116
	v_mul_f32_e32 v145, 0xbfb8aa3b, v117
	v_mul_f32_e32 v138, 0xbfb8aa3b, v118
	v_mul_f32_e32 v146, 0xbfb8aa3b, v119
	v_mul_f32_e32 v139, 0xbfb8aa3b, v120
	v_mul_f32_e32 v147, 0xbfb8aa3b, v121
	v_mul_f32_e32 v140, 0xbfb8aa3b, v122
	v_mul_f32_e32 v148, 0xbfb8aa3b, v123
	v_mul_f32_e32 v141, 0xbfb8aa3b, v124
	v_mul_f32_e32 v149, 0xbfb8aa3b, v125
	v_exp_f32_e32 v134, v134
	v_exp_f32_e32 v142, v142
	v_exp_f32_e32 v135, v135
	v_exp_f32_e32 v143, v143
	v_exp_f32_e32 v136, v136
	v_exp_f32_e32 v144, v144
	v_exp_f32_e32 v137, v137
	v_exp_f32_e32 v145, v145
	v_exp_f32_e32 v138, v138
	v_exp_f32_e32 v146, v146
	v_exp_f32_e32 v139, v139
	v_exp_f32_e32 v147, v147
	v_exp_f32_e32 v140, v140
	v_exp_f32_e32 v148, v148
	v_exp_f32_e32 v141, v141
	v_exp_f32_e32 v149, v149
	s_nop 0
	v_add_f32_e32 v134, 1.0, v134
	v_add_f32_e32 v142, 1.0, v142
	v_add_f32_e32 v135, 1.0, v135
	v_add_f32_e32 v143, 1.0, v143
	v_add_f32_e32 v136, 1.0, v136
	v_add_f32_e32 v144, 1.0, v144
	v_add_f32_e32 v137, 1.0, v137
	v_add_f32_e32 v145, 1.0, v145
	v_add_f32_e32 v138, 1.0, v138
	v_add_f32_e32 v146, 1.0, v146
	v_add_f32_e32 v139, 1.0, v139
	v_add_f32_e32 v147, 1.0, v147
	v_add_f32_e32 v140, 1.0, v140
	v_add_f32_e32 v148, 1.0, v148
	v_add_f32_e32 v141, 1.0, v141
	v_add_f32_e32 v149, 1.0, v149
	v_rcp_f32_e32 v134, v134
	v_rcp_f32_e32 v142, v142
	v_rcp_f32_e32 v135, v135
	v_rcp_f32_e32 v143, v143
	v_rcp_f32_e32 v136, v136
	v_rcp_f32_e32 v144, v144
	v_rcp_f32_e32 v137, v137
	v_rcp_f32_e32 v145, v145
	v_rcp_f32_e32 v138, v138
	v_rcp_f32_e32 v146, v146
	v_rcp_f32_e32 v139, v139
	v_rcp_f32_e32 v147, v147
	v_rcp_f32_e32 v140, v140
	v_rcp_f32_e32 v148, v148
	v_rcp_f32_e32 v141, v141
	v_rcp_f32_e32 v149, v149
	s_nop 0
	v_mul_f32_e32 v110, v110, v134
	v_mul_f32_e32 v111, v111, v142
	v_mul_f32_e32 v112, v112, v135
	v_mul_f32_e32 v113, v113, v143
	v_mul_f32_e32 v114, v114, v136
	v_mul_f32_e32 v115, v115, v144
	v_mul_f32_e32 v116, v116, v137
	v_mul_f32_e32 v117, v117, v145
	v_mul_f32_e32 v118, v118, v138
	v_mul_f32_e32 v119, v119, v146
	v_mul_f32_e32 v120, v120, v139
	v_mul_f32_e32 v121, v121, v147
	v_mul_f32_e32 v122, v122, v140
	v_mul_f32_e32 v123, v123, v148
	v_mul_f32_e32 v124, v124, v141
	v_mul_f32_e32 v125, v125, v149
	v_cvt_pk_bf16_f32 v134, v110, v111
	v_cvt_pk_bf16_f32 v135, v112, v113
	v_cvt_pk_bf16_f32 v136, v114, v115
	v_cvt_pk_bf16_f32 v137, v116, v117
	v_cvt_pk_bf16_f32 v138, v118, v119
	v_cvt_pk_bf16_f32 v139, v120, v121
	v_cvt_pk_bf16_f32 v140, v122, v123
	v_cvt_pk_bf16_f32 v141, v124, v125
	v_add_u32_e32 v66, s31, v41
	v_ashrrev_i32_e32 v67, 31, v66
	v_lshlrev_b64 v[66:67], 12, v[66:67]
	v_lshl_add_u64 v[66:67], s[92:93], 0, v[66:67]
	v_lshl_add_u64 v[66:67], v[66:67], 0, s[26:27]
	v_lshl_add_u64 v[66:67], v[66:67], 0, v[30:31]
	global_store_dword v[66:67], v134, off offset:2048
	v_add_u32_e32 v66, s31, v51
	v_ashrrev_i32_e32 v67, 31, v66
	v_lshlrev_b64 v[66:67], 12, v[66:67]
	v_lshl_add_u64 v[66:67], s[92:93], 0, v[66:67]
	v_lshl_add_u64 v[66:67], v[66:67], 0, s[26:27]
	v_lshl_add_u64 v[66:67], v[66:67], 0, v[30:31]
	global_store_dword v[66:67], v135, off offset:2048
	v_add_u32_e32 v66, s31, v52
	v_ashrrev_i32_e32 v67, 31, v66
	v_lshlrev_b64 v[66:67], 12, v[66:67]
	v_lshl_add_u64 v[66:67], s[92:93], 0, v[66:67]
	v_lshl_add_u64 v[66:67], v[66:67], 0, s[26:27]
	v_lshl_add_u64 v[66:67], v[66:67], 0, v[30:31]
	global_store_dword v[66:67], v136, off offset:2048
	v_add_u32_e32 v66, s31, v53
	v_ashrrev_i32_e32 v67, 31, v66
	v_lshlrev_b64 v[66:67], 12, v[66:67]
	v_lshl_add_u64 v[66:67], s[92:93], 0, v[66:67]
	v_lshl_add_u64 v[66:67], v[66:67], 0, s[26:27]
	v_lshl_add_u64 v[66:67], v[66:67], 0, v[30:31]
	global_store_dword v[66:67], v137, off offset:2048
	v_add_u32_e32 v66, s31, v54
	v_ashrrev_i32_e32 v67, 31, v66
	v_lshlrev_b64 v[66:67], 12, v[66:67]
	v_lshl_add_u64 v[66:67], s[92:93], 0, v[66:67]
	v_lshl_add_u64 v[66:67], v[66:67], 0, s[26:27]
	v_lshl_add_u64 v[66:67], v[66:67], 0, v[30:31]
	global_store_dword v[66:67], v138, off offset:2048
	v_add_u32_e32 v66, s31, v55
	v_ashrrev_i32_e32 v67, 31, v66
	v_lshlrev_b64 v[66:67], 12, v[66:67]
	v_lshl_add_u64 v[66:67], s[92:93], 0, v[66:67]
	v_lshl_add_u64 v[66:67], v[66:67], 0, s[26:27]
	v_lshl_add_u64 v[66:67], v[66:67], 0, v[30:31]
	global_store_dword v[66:67], v139, off offset:2048
	v_add_u32_e32 v66, s31, v56
	v_ashrrev_i32_e32 v67, 31, v66
	v_lshlrev_b64 v[66:67], 12, v[66:67]
	v_lshl_add_u64 v[66:67], s[92:93], 0, v[66:67]
	v_lshl_add_u64 v[66:67], v[66:67], 0, s[26:27]
	v_lshl_add_u64 v[66:67], v[66:67], 0, v[30:31]
	global_store_dword v[66:67], v140, off offset:2048
	v_add_u32_e32 v66, s31, v57
	v_ashrrev_i32_e32 v67, 31, v66
	v_lshlrev_b64 v[66:67], 12, v[66:67]
	v_lshl_add_u64 v[66:67], s[92:93], 0, v[66:67]
	v_lshl_add_u64 v[66:67], v[66:67], 0, s[26:27]
	v_lshl_add_u64 v[66:67], v[66:67], 0, v[30:31]
	global_store_dword v[66:67], v141, off offset:2048
	s_cbranch_vccz .LBB0_186

; #define PG8_STAGE(bufoff, gbase, voff) do { _Pragma("unroll") for (int _i = 0; _i < 2; ++_i) \
;         __builtin_amdgcn_global_load_lds((const unsigned*)((const char*)(gbase) + (voff)[_i]), (LAS unsigned*)(lds + (bufoff) + ldsw + _i * 8192), 16, 0, 0); } while (0)
; #define PG8_LDA(dst, b, h) do { _Pragma("unroll") for (int m = 0; m < 4; ++m) _Pragma("unroll") for (int k = 0; k < 2; ++k) dst[m][k] = *(const LAS bf16x8*)(lds + PG8_SA(b, h) + aoff + m * 2048 + k * 1024); } while (0)
; #define PG8_LDB(dst, b, h) do { _Pragma("unroll") for (int n = 0; n < 2; ++n) _Pragma("unroll") for (int k = 0; k < 2; ++k) dst[n][k] = *(const LAS bf16x8*)(lds + PG8_SB(b, h) + boff + n * 2048 + k * 1024); } while (0)
; #define PG8_MMA(ai, bj, At, Bt) do { __builtin_amdgcn_s_setprio(3); _Pragma("unroll") for (int m = 0; m < 4; ++m) _Pragma("unroll") for (int n = 0; n < 2; ++n) _Pragma("unroll") for (int k = 0; k < 2; ++k) \
;         acc[ai][bj][m][n] = __builtin_amdgcn_mfma_f32_16x16x32_bf16(Bt[n][k], At[m][k], acc[ai][bj][m][n], 0, 0, 0); __builtin_amdgcn_s_setprio(0); } while (0)
; #define PG8_WAIT_V(n) asm volatile("s_waitcnt vmcnt(" #n ")" ::: "memory")
; #define PG8_WAIT_L(n) asm volatile("s_waitcnt lgkmcnt(" #n ")" ::: "memory")
; #define PG8_BAR __builtin_amdgcn_s_barrier()
; #define PG8_SCHED __builtin_amdgcn_sched_barrier(0)
; template <class Epi>
; __device__ __forceinline__ void gemm_phase(LAS unsigned char* lds, const Gemm g, const StaticOrder& S, const Epi& E, const int tid) {
;     ...
;             PG8_LDB(B0, 0, 0); PG8_LDB(B1, 0, 1); PG8_SCHED; PG8_LDA(At, 0, 0); PG8_STAGE(PG8_SA(1, 1), a1 + hstepA, voffA);
;             PG8_WAIT_V(8); PG8_WAIT_L(0); PG8_BAR; PG8_MMA(0, 0, At, B0); PG8_MMA(0, 1, At, B1); PG8_BAR; PG8_SCHED;
;             PG8_LDA(At, 0, 1); PG8_STAGE(PG8_SB(0, 0), b2, voffB); PG8_STAGE(PG8_SB(0, 1), b2 + hstepB, voffB); PG8_STAGE(PG8_SA(0, 0), a2, voffA);
;             PG8_WAIT_V(8); PG8_WAIT_L(0); PG8_BAR; PG8_MMA(1, 0, At, B0); PG8_MMA(1, 1, At, B1); PG8_BAR; PG8_SCHED;
.LBB0_264:
	s_add_u32 s30, s6, 0x100
	s_addc_u32 s31, s7, 0
	s_add_u32 s4, s20, 0x80
	s_addc_u32 s5, s21, 0
	s_mov_b32 s6, 0
	s_add_i32 s20, s6, 2
	s_add_u32 s21, s4, 0x80
	s_addc_u32 s7, s5, 0
	s_add_i32 s55, 0, 0x10000
	s_cmp_eq_u32 s48, s6
	s_cselect_b32 s7, s79, s7
	s_cselect_b32 s6, s78, s21
	s_cselect_b32 vcc_hi, s81, s31
	s_cselect_b32 vcc_lo, s80, s30
	s_add_i32 s21, 0, 0x14000
	v_add_u32_e32 v152, s55, v169
	v_add_u32_e32 v156, s21, v169
	ds_read_b128 v[140:143], v152
	ds_read_b128 v[144:147], v152 offset:1024
	ds_read_b128 v[148:151], v152 offset:2048
	ds_read_b128 v[152:155], v152 offset:3072
	ds_read_b128 v[172:175], v156
	ds_read_b128 v[180:183], v156 offset:1024
	ds_read_b128 v[184:187], v156 offset:2048
	ds_read_b128 v[194:197], v156 offset:3072
	v_lshl_add_u64 v[156:157], s[4:5], 0, v[138:139]
	s_add_i32 m0, s94, 0xc000
	ds_read_b128 v[198:201], v171
	ds_read_b128 v[202:205], v171 offset:1024
	ds_read_b128 v[206:209], v171 offset:2048
	ds_read_b128 v[210:213], v171 offset:3072
	ds_read_b128 v[214:217], v171 offset:4096
	ds_read_b128 v[218:221], v171 offset:5120
	ds_read_b128 v[222:225], v171 offset:6144
	ds_read_b128 v[226:229], v171 offset:7168
	global_load_lds_dwordx4 v[156:157], off
	v_lshl_add_u64 v[156:157], s[4:5], 0, v[136:137]
	s_add_i32 m0, s94, 0xe000
	s_nop 0
	global_load_lds_dwordx4 v[156:157], off
	s_waitcnt vmcnt(8)
	s_waitcnt lgkmcnt(0)
	s_barrier
	s_setprio 3
	s_waitcnt lgkmcnt(0)
	v_mfma_f32_16x16x32_bf16 v[124:127], v[140:143], v[198:201], 0
	v_mfma_f32_16x16x32_bf16 v[120:123], v[148:151], v[198:201], 0
	v_mfma_f32_16x16x32_bf16 v[116:119], v[140:143], v[206:209], 0
	v_mfma_f32_16x16x32_bf16 v[108:111], v[148:151], v[206:209], 0
	v_mfma_f32_16x16x32_bf16 v[100:103], v[140:143], v[214:217], 0
	v_mfma_f32_16x16x32_bf16 v[92:95], v[148:151], v[214:217], 0
	v_mfma_f32_16x16x32_bf16 v[84:87], v[140:143], v[222:225], 0
	v_mfma_f32_16x16x32_bf16 v[76:79], v[148:151], v[222:225], 0
	v_mfma_f32_16x16x32_bf16 v[124:127], v[144:147], v[202:205], v[124:127]
	v_mfma_f32_16x16x32_bf16 v[120:123], v[152:155], v[202:205], v[120:123]
	v_mfma_f32_16x16x32_bf16 v[116:119], v[144:147], v[210:213], v[116:119]
	v_mfma_f32_16x16x32_bf16 v[108:111], v[152:155], v[210:213], v[108:111]
	v_mfma_f32_16x16x32_bf16 v[100:103], v[144:147], v[218:221], v[100:103]
	v_mfma_f32_16x16x32_bf16 v[92:95], v[152:155], v[218:221], v[92:95]
	v_mfma_f32_16x16x32_bf16 v[84:87], v[144:147], v[226:229], v[84:87]
	v_mfma_f32_16x16x32_bf16 v[76:79], v[152:155], v[226:229], v[76:79]
	s_setprio 0
	s_setprio 3
	v_mfma_f32_16x16x32_bf16 v[112:115], v[172:175], v[198:201], 0
	v_mfma_f32_16x16x32_bf16 v[104:107], v[184:187], v[198:201], 0
	v_mfma_f32_16x16x32_bf16 v[96:99], v[172:175], v[206:209], 0
	v_mfma_f32_16x16x32_bf16 v[88:91], v[184:187], v[206:209], 0
	v_mfma_f32_16x16x32_bf16 v[80:83], v[172:175], v[214:217], 0
	v_mfma_f32_16x16x32_bf16 v[72:75], v[184:187], v[214:217], 0
	v_mfma_f32_16x16x32_bf16 v[68:71], v[172:175], v[222:225], 0
	v_mfma_f32_16x16x32_bf16 v[64:67], v[184:187], v[222:225], 0
	v_mfma_f32_16x16x32_bf16 v[112:115], v[180:183], v[202:205], v[112:115]
	v_mfma_f32_16x16x32_bf16 v[104:107], v[194:197], v[202:205], v[104:107]
	v_mfma_f32_16x16x32_bf16 v[96:99], v[180:183], v[210:213], v[96:99]
	v_mfma_f32_16x16x32_bf16 v[88:91], v[194:197], v[210:213], v[88:91]
	v_mfma_f32_16x16x32_bf16 v[80:83], v[180:183], v[218:221], v[80:83]
	v_mfma_f32_16x16x32_bf16 v[72:75], v[194:197], v[218:221], v[72:75]
	v_mfma_f32_16x16x32_bf16 v[68:71], v[180:183], v[226:229], v[68:71]
	v_mfma_f32_16x16x32_bf16 v[64:67], v[194:197], v[226:229], v[64:67]
	s_setprio 0
	s_barrier
	s_add_i32 s55, s55, s93
	v_lshl_add_u64 v[156:157], vcc, 0, v[130:131]
	s_mov_b32 m0, s55
	ds_read_b128 v[198:201], v171 offset:16384
	ds_read_b128 v[202:205], v171 offset:17408
	ds_read_b128 v[206:209], v171 offset:18432
	ds_read_b128 v[210:213], v171 offset:19456
	ds_read_b128 v[214:217], v171 offset:20480
	ds_read_b128 v[218:221], v171 offset:21504
	ds_read_b128 v[222:225], v171 offset:22528
	ds_read_b128 v[226:229], v171 offset:23552
	global_load_lds_dwordx4 v[156:157], off
	s_add_i32 m0, s55, 0x2000
	v_lshl_add_u64 v[190:191], vcc, 0, v[134:135]
	s_add_u32 vcc_lo, vcc_lo, s91
	s_addc_u32 vcc_hi, vcc_hi, 0
	s_add_i32 s21, s21, s93
	global_load_lds_dwordx4 v[190:191], off
	v_lshl_add_u64 v[240:241], vcc, 0, v[130:131]
	s_mov_b32 m0, s21
	v_lshl_add_u64 v[242:243], vcc, 0, v[134:135]
	global_load_lds_dwordx4 v[240:241], off
	s_add_i32 m0, s21, 0x2000
	v_lshl_add_u64 v[244:245], s[6:7], 0, v[128:129]
	global_load_lds_dwordx4 v[242:243], off
	s_mov_b32 m0, s94
	v_lshl_add_u64 v[246:247], s[6:7], 0, v[132:133]
	global_load_lds_dwordx4 v[244:245], off
	s_mov_b32 m0, s95
	s_nop 0
	global_load_lds_dwordx4 v[246:247], off
	s_waitcnt vmcnt(8)
	s_waitcnt lgkmcnt(0)
	s_barrier
; #define PG8_STAGE(bufoff, gbase, voff) do { _Pragma("unroll") for (int _i = 0; _i < 2; ++_i) \
;         __builtin_amdgcn_global_load_lds((const unsigned*)((const char*)(gbase) + (voff)[_i]), (LAS unsigned*)(lds + (bufoff) + ldsw + _i * 8192), 16, 0, 0); } while (0)
; #define PG8_LDA(dst, b, h) do { _Pragma("unroll") for (int m = 0; m < 4; ++m) _Pragma("unroll") for (int k = 0; k < 2; ++k) dst[m][k] = *(const LAS bf16x8*)(lds + PG8_SA(b, h) + aoff + m * 2048 + k * 1024); } while (0)
; #define PG8_LDB(dst, b, h) do { _Pragma("unroll") for (int n = 0; n < 2; ++n) _Pragma("unroll") for (int k = 0; k < 2; ++k) dst[n][k] = *(const LAS bf16x8*)(lds + PG8_SB(b, h) + boff + n * 2048 + k * 1024); } while (0)
; #define PG8_MMA(ai, bj, At, Bt) do { __builtin_amdgcn_s_setprio(3); _Pragma("unroll") for (int m = 0; m < 4; ++m) _Pragma("unroll") for (int n = 0; n < 2; ++n) _Pragma("unroll") for (int k = 0; k < 2; ++k) \
;         acc[ai][bj][m][n] = __builtin_amdgcn_mfma_f32_16x16x32_bf16(Bt[n][k], At[m][k], acc[ai][bj][m][n], 0, 0, 0); __builtin_amdgcn_s_setprio(0); } while (0)
; #define PG8_WAIT_V(n) asm volatile("s_waitcnt vmcnt(" #n ")" ::: "memory")
; #define PG8_WAIT_L(n) asm volatile("s_waitcnt lgkmcnt(" #n ")" ::: "memory")
; #define PG8_BAR __builtin_amdgcn_s_barrier()
; #define PG8_SCHED __builtin_amdgcn_sched_barrier(0)
; template <class Epi>
; __device__ __forceinline__ void gemm_phase(LAS unsigned char* lds, const Gemm g, const StaticOrder& S, const Epi& E, const int tid) {
;     ...
;             PG8_WAIT_V(8); PG8_WAIT_L(0); PG8_BAR; PG8_MMA(1, 0, At, B0); PG8_MMA(1, 1, At, B1); PG8_BAR; PG8_SCHED;
;             PG8_LDB(B0, 1, 0); PG8_LDB(B1, 1, 1); PG8_SCHED; PG8_LDA(At, 1, 0); PG8_STAGE(PG8_SA(0, 1), a2 + hstepA, voffA);
;             PG8_WAIT_V(8); PG8_WAIT_L(0); PG8_BAR; PG8_MMA(0, 0, At, B0); PG8_MMA(0, 1, At, B1); PG8_BAR; PG8_SCHED;
	s_setprio 3
	s_waitcnt lgkmcnt(0)
	v_mfma_f32_16x16x32_bf16 v[60:63], v[140:143], v[198:201], 0
	v_mfma_f32_16x16x32_bf16 v[56:59], v[148:151], v[198:201], 0
	v_mfma_f32_16x16x32_bf16 v[48:51], v[140:143], v[206:209], 0
	v_mfma_f32_16x16x32_bf16 v[40:43], v[148:151], v[206:209], 0
	v_mfma_f32_16x16x32_bf16 v[32:35], v[140:143], v[214:217], 0
	v_mfma_f32_16x16x32_bf16 v[24:27], v[148:151], v[214:217], 0
	v_mfma_f32_16x16x32_bf16 v[16:19], v[140:143], v[222:225], 0
	v_mfma_f32_16x16x32_bf16 v[8:11], v[148:151], v[222:225], 0
	v_mfma_f32_16x16x32_bf16 v[60:63], v[144:147], v[202:205], v[60:63]
	v_mfma_f32_16x16x32_bf16 v[56:59], v[152:155], v[202:205], v[56:59]
	v_mfma_f32_16x16x32_bf16 v[48:51], v[144:147], v[210:213], v[48:51]
	v_mfma_f32_16x16x32_bf16 v[40:43], v[152:155], v[210:213], v[40:43]
	v_mfma_f32_16x16x32_bf16 v[32:35], v[144:147], v[218:221], v[32:35]
	v_mfma_f32_16x16x32_bf16 v[24:27], v[152:155], v[218:221], v[24:27]
	v_mfma_f32_16x16x32_bf16 v[16:19], v[144:147], v[226:229], v[16:19]
	v_mfma_f32_16x16x32_bf16 v[8:11], v[152:155], v[226:229], v[8:11]
	s_setprio 0
	s_setprio 3
	v_mfma_f32_16x16x32_bf16 v[52:55], v[172:175], v[198:201], 0
	v_mfma_f32_16x16x32_bf16 v[44:47], v[184:187], v[198:201], 0
	v_mfma_f32_16x16x32_bf16 v[36:39], v[172:175], v[206:209], 0
	v_mfma_f32_16x16x32_bf16 v[28:31], v[184:187], v[206:209], 0
	v_mfma_f32_16x16x32_bf16 v[20:23], v[172:175], v[214:217], 0
	v_mfma_f32_16x16x32_bf16 v[12:15], v[184:187], v[214:217], 0
	v_mfma_f32_16x16x32_bf16 v[4:7], v[172:175], v[222:225], 0
	v_mfma_f32_16x16x32_bf16 v[0:3], v[184:187], v[222:225], 0
	v_mfma_f32_16x16x32_bf16 v[52:55], v[180:183], v[202:205], v[52:55]
	v_mfma_f32_16x16x32_bf16 v[44:47], v[194:197], v[202:205], v[44:47]
	v_mfma_f32_16x16x32_bf16 v[36:39], v[180:183], v[210:213], v[36:39]
	v_mfma_f32_16x16x32_bf16 v[28:31], v[194:197], v[210:213], v[28:31]
	v_mfma_f32_16x16x32_bf16 v[20:23], v[180:183], v[218:221], v[20:23]
	v_mfma_f32_16x16x32_bf16 v[12:15], v[194:197], v[218:221], v[12:15]
	v_mfma_f32_16x16x32_bf16 v[4:7], v[180:183], v[226:229], v[4:7]
	v_mfma_f32_16x16x32_bf16 v[0:3], v[194:197], v[226:229], v[0:3]
	s_setprio 0
	s_barrier
	s_add_i32 s21, 0, 0x18000
	s_add_i32 s55, 0, 0x1c000
	v_add_u32_e32 v152, s21, v169
	v_add_u32_e32 v176, s55, v169
	ds_read_b128 v[140:143], v152
	ds_read_b128 v[144:147], v152 offset:1024
	ds_read_b128 v[148:151], v152 offset:2048
	ds_read_b128 v[152:155], v152 offset:3072
	ds_read_b128 v[172:175], v176
	ds_read_b128 v[180:183], v176 offset:1024
	ds_read_b128 v[184:187], v176 offset:2048
	ds_read_b128 v[194:197], v176 offset:3072
	s_add_u32 s6, s6, s26
	s_addc_u32 s7, s7, 0
	s_mov_b32 m0, s96
	v_lshl_add_u64 v[252:253], s[6:7], 0, v[128:129]
	ds_read_b128 v[198:201], v171 offset:32768
	ds_read_b128 v[202:205], v171 offset:33792
	ds_read_b128 v[206:209], v171 offset:34816
	ds_read_b128 v[210:213], v171 offset:35840
	ds_read_b128 v[214:217], v171 offset:36864
	ds_read_b128 v[218:221], v171 offset:37888
	ds_read_b128 v[222:225], v171 offset:38912
	ds_read_b128 v[226:229], v171 offset:39936
	global_load_lds_dwordx4 v[252:253], off
	v_lshl_add_u64 v[252:253], s[6:7], 0, v[132:133]
	s_mov_b32 m0, s97
	s_nop 0
	global_load_lds_dwordx4 v[252:253], off
	s_waitcnt vmcnt(8)
	s_waitcnt lgkmcnt(0)
	s_barrier
	s_setprio 3
	s_waitcnt lgkmcnt(0)
	v_mfma_f32_16x16x32_bf16 v[124:127], v[140:143], v[198:201], v[124:127]
	v_mfma_f32_16x16x32_bf16 v[120:123], v[148:151], v[198:201], v[120:123]
	v_mfma_f32_16x16x32_bf16 v[116:119], v[140:143], v[206:209], v[116:119]
	v_mfma_f32_16x16x32_bf16 v[108:111], v[148:151], v[206:209], v[108:111]
	v_mfma_f32_16x16x32_bf16 v[100:103], v[140:143], v[214:217], v[100:103]
	v_mfma_f32_16x16x32_bf16 v[92:95], v[148:151], v[214:217], v[92:95]
	v_mfma_f32_16x16x32_bf16 v[84:87], v[140:143], v[222:225], v[84:87]
	v_mfma_f32_16x16x32_bf16 v[76:79], v[148:151], v[222:225], v[76:79]
	v_mfma_f32_16x16x32_bf16 v[124:127], v[144:147], v[202:205], v[124:127]
	v_mfma_f32_16x16x32_bf16 v[120:123], v[152:155], v[202:205], v[120:123]
	v_mfma_f32_16x16x32_bf16 v[116:119], v[144:147], v[210:213], v[116:119]
	v_mfma_f32_16x16x32_bf16 v[108:111], v[152:155], v[210:213], v[108:111]
	v_mfma_f32_16x16x32_bf16 v[100:103], v[144:147], v[218:221], v[100:103]
	v_mfma_f32_16x16x32_bf16 v[92:95], v[152:155], v[218:221], v[92:95]
	v_mfma_f32_16x16x32_bf16 v[84:87], v[144:147], v[226:229], v[84:87]
	v_mfma_f32_16x16x32_bf16 v[76:79], v[152:155], v[226:229], v[76:79]
	s_setprio 0
	s_setprio 3
	v_mfma_f32_16x16x32_bf16 v[112:115], v[172:175], v[198:201], v[112:115]
	v_mfma_f32_16x16x32_bf16 v[104:107], v[184:187], v[198:201], v[104:107]
	v_mfma_f32_16x16x32_bf16 v[96:99], v[172:175], v[206:209], v[96:99]
	v_mfma_f32_16x16x32_bf16 v[88:91], v[184:187], v[206:209], v[88:91]
	v_mfma_f32_16x16x32_bf16 v[80:83], v[172:175], v[214:217], v[80:83]
	v_mfma_f32_16x16x32_bf16 v[72:75], v[184:187], v[214:217], v[72:75]
	v_mfma_f32_16x16x32_bf16 v[68:71], v[172:175], v[222:225], v[68:71]
	v_mfma_f32_16x16x32_bf16 v[64:67], v[184:187], v[222:225], v[64:67]
	v_mfma_f32_16x16x32_bf16 v[112:115], v[180:183], v[202:205], v[112:115]
	v_mfma_f32_16x16x32_bf16 v[104:107], v[194:197], v[202:205], v[104:107]
	v_mfma_f32_16x16x32_bf16 v[96:99], v[180:183], v[210:213], v[96:99]
	v_mfma_f32_16x16x32_bf16 v[88:91], v[194:197], v[210:213], v[88:91]
	v_mfma_f32_16x16x32_bf16 v[80:83], v[180:183], v[218:221], v[80:83]
	v_mfma_f32_16x16x32_bf16 v[72:75], v[194:197], v[218:221], v[72:75]
	v_mfma_f32_16x16x32_bf16 v[68:71], v[180:183], v[226:229], v[68:71]
	v_mfma_f32_16x16x32_bf16 v[64:67], v[194:197], v[226:229], v[64:67]
	s_setprio 0
	s_barrier
; #define PG8_STAGE(bufoff, gbase, voff) do { _Pragma("unroll") for (int _i = 0; _i < 2; ++_i) \
;         __builtin_amdgcn_global_load_lds((const unsigned*)((const char*)(gbase) + (voff)[_i]), (LAS unsigned*)(lds + (bufoff) + ldsw + _i * 8192), 16, 0, 0); } while (0)
; #define PG8_LDA(dst, b, h) do { _Pragma("unroll") for (int m = 0; m < 4; ++m) _Pragma("unroll") for (int k = 0; k < 2; ++k) dst[m][k] = *(const LAS bf16x8*)(lds + PG8_SA(b, h) + aoff + m * 2048 + k * 1024); } while (0)
; #define PG8_MMA(ai, bj, At, Bt) do { __builtin_amdgcn_s_setprio(3); _Pragma("unroll") for (int m = 0; m < 4; ++m) _Pragma("unroll") for (int n = 0; n < 2; ++n) _Pragma("unroll") for (int k = 0; k < 2; ++k) \
;         acc[ai][bj][m][n] = __builtin_amdgcn_mfma_f32_16x16x32_bf16(Bt[n][k], At[m][k], acc[ai][bj][m][n], 0, 0, 0); __builtin_amdgcn_s_setprio(0); } while (0)
; #define PG8_WAIT_V(n) asm volatile("s_waitcnt vmcnt(" #n ")" ::: "memory")
; #define PG8_WAIT_L(n) asm volatile("s_waitcnt lgkmcnt(" #n ")" ::: "memory")
; #define PG8_BAR __builtin_amdgcn_s_barrier()
; #define PG8_SCHED __builtin_amdgcn_sched_barrier(0)
; template <class Epi>
; __device__ __forceinline__ void gemm_phase(LAS unsigned char* lds, const Gemm g, const StaticOrder& S, const Epi& E, const int tid) {
;     ...
;         for (int t = 0; t < nt; t += 2) {
;             const bool last = (t == nt - 2);
;             const char* a1 = cA + (size_t)(t + 1) * kstep;
;             const char* a2 = last ? nA : cA + (size_t)(t + 2) * kstep; const char* b2 = last ? nB : cB + (size_t)(t + 2) * kstep;
;             const char* a3 = a2 + kstep; const char* b3 = b2 + kstep;
;     ...
;             PG8_LDA(At, 1, 1); PG8_STAGE(PG8_SB(1, 0), b3, voffB); PG8_STAGE(PG8_SB(1, 1), b3 + hstepB, voffB); PG8_STAGE(PG8_SA(1, 0), a3, voffA);
;             PG8_WAIT_V(8); PG8_WAIT_L(0); PG8_BAR; PG8_MMA(1, 0, At, B0); PG8_MMA(1, 1, At, B1); PG8_BAR; PG8_SCHED;
;         }
	s_add_i32 s6, s21, s93
	v_lshl_add_u64 v[156:157], v[156:157], 0, s[22:23]
	s_mov_b32 m0, s6
	ds_read_b128 v[198:201], v171 offset:49152
	ds_read_b128 v[202:205], v171 offset:50176
	ds_read_b128 v[206:209], v171 offset:51200
	ds_read_b128 v[210:213], v171 offset:52224
	ds_read_b128 v[214:217], v171 offset:53248
	ds_read_b128 v[218:221], v171 offset:54272
	ds_read_b128 v[222:225], v171 offset:55296
	ds_read_b128 v[226:229], v171 offset:56320
	global_load_lds_dwordx4 v[156:157], off
	v_lshl_add_u64 v[156:157], v[190:191], 0, s[22:23]
	s_add_i32 m0, s6, 0x2000
	s_add_i32 s6, s55, s93
	global_load_lds_dwordx4 v[156:157], off
	v_lshl_add_u64 v[156:157], v[240:241], 0, s[22:23]
	s_mov_b32 m0, s6
	s_nop 0
	global_load_lds_dwordx4 v[156:157], off
	v_lshl_add_u64 v[156:157], v[242:243], 0, s[22:23]
	s_add_i32 m0, s6, 0x2000
	s_nop 0
	global_load_lds_dwordx4 v[156:157], off
	v_lshl_add_u64 v[156:157], v[244:245], 0, s[22:23]
	s_mov_b32 m0, s98
	s_nop 0
	global_load_lds_dwordx4 v[156:157], off
	v_lshl_add_u64 v[156:157], v[246:247], 0, s[22:23]
	s_mov_b32 m0, s99
	s_nop 0
	global_load_lds_dwordx4 v[156:157], off
	s_waitcnt vmcnt(8)
	s_waitcnt lgkmcnt(0)
	s_barrier
	s_setprio 3
	s_waitcnt lgkmcnt(0)
	v_mfma_f32_16x16x32_bf16 v[60:63], v[140:143], v[198:201], v[60:63]
	v_mfma_f32_16x16x32_bf16 v[56:59], v[148:151], v[198:201], v[56:59]
	v_mfma_f32_16x16x32_bf16 v[48:51], v[140:143], v[206:209], v[48:51]
	v_mfma_f32_16x16x32_bf16 v[40:43], v[148:151], v[206:209], v[40:43]
	v_mfma_f32_16x16x32_bf16 v[32:35], v[140:143], v[214:217], v[32:35]
	v_mfma_f32_16x16x32_bf16 v[24:27], v[148:151], v[214:217], v[24:27]
	v_mfma_f32_16x16x32_bf16 v[16:19], v[140:143], v[222:225], v[16:19]
	v_mfma_f32_16x16x32_bf16 v[8:11], v[148:151], v[222:225], v[8:11]
	v_mfma_f32_16x16x32_bf16 v[60:63], v[144:147], v[202:205], v[60:63]
	v_mfma_f32_16x16x32_bf16 v[56:59], v[152:155], v[202:205], v[56:59]
	v_mfma_f32_16x16x32_bf16 v[48:51], v[144:147], v[210:213], v[48:51]
	v_mfma_f32_16x16x32_bf16 v[40:43], v[152:155], v[210:213], v[40:43]
	v_mfma_f32_16x16x32_bf16 v[32:35], v[144:147], v[218:221], v[32:35]
	v_mfma_f32_16x16x32_bf16 v[24:27], v[152:155], v[218:221], v[24:27]
	v_mfma_f32_16x16x32_bf16 v[16:19], v[144:147], v[226:229], v[16:19]
	v_mfma_f32_16x16x32_bf16 v[8:11], v[152:155], v[226:229], v[8:11]
	s_setprio 0
	s_setprio 3
	v_mfma_f32_16x16x32_bf16 v[52:55], v[172:175], v[198:201], v[52:55]
	v_mfma_f32_16x16x32_bf16 v[44:47], v[184:187], v[198:201], v[44:47]
	v_mfma_f32_16x16x32_bf16 v[36:39], v[172:175], v[206:209], v[36:39]
	v_mfma_f32_16x16x32_bf16 v[28:31], v[184:187], v[206:209], v[28:31]
	v_mfma_f32_16x16x32_bf16 v[20:23], v[172:175], v[214:217], v[20:23]
	v_mfma_f32_16x16x32_bf16 v[12:15], v[184:187], v[214:217], v[12:15]
	v_mfma_f32_16x16x32_bf16 v[4:7], v[172:175], v[222:225], v[4:7]
	v_mfma_f32_16x16x32_bf16 v[0:3], v[184:187], v[222:225], v[0:3]
	v_mfma_f32_16x16x32_bf16 v[52:55], v[180:183], v[202:205], v[52:55]
	v_mfma_f32_16x16x32_bf16 v[44:47], v[194:197], v[202:205], v[44:47]
	v_mfma_f32_16x16x32_bf16 v[36:39], v[180:183], v[210:213], v[36:39]
	v_mfma_f32_16x16x32_bf16 v[28:31], v[194:197], v[210:213], v[28:31]
	v_mfma_f32_16x16x32_bf16 v[20:23], v[180:183], v[218:221], v[20:23]
	v_mfma_f32_16x16x32_bf16 v[12:15], v[194:197], v[218:221], v[12:15]
	v_mfma_f32_16x16x32_bf16 v[4:7], v[180:183], v[226:229], v[4:7]
	v_mfma_f32_16x16x32_bf16 v[0:3], v[194:197], v[226:229], v[0:3]
	s_setprio 0
	s_barrier
	s_add_u32 s30, s30, 0x100
	s_addc_u32 s31, s31, 0
	s_add_u32 s4, s4, 0x100
	s_addc_u32 s5, s5, 0
	s_cmp_ge_u32 s20, s89
	s_mov_b32 s6, s20
	s_cbranch_scc1 .Lpg_kloop_done

; #define PG8_BAR __builtin_amdgcn_s_barrier()
; template <class Epi>
; __device__ __forceinline__ void gemm_phase(LAS unsigned char* lds, const Gemm g, const StaticOrder& S, const Epi& E, const int tid) {
;     ...
;         if (wr == 0) PG8_BAR;
;         E(acc, cur, wr, wc, fr, fq);
.Lpg_kloop_done:
	s_and_b64 vcc, exec, s[76:77]
	s_cbranch_vccnz .LBB0_269
	v_lshl_add_u32 v140, s50, 8, v168
	s_cmp_lt_i32 s90, 2
	s_mov_b64 s[4:5], -1
	s_cbranch_scc0 .LBB0_270
